# fix: K fragments prefetched across the barrier in a unit's first fast iteration are re-read behind the barrier (the compiled code issued that tile only one iteration earlier); plus DPP sub-LN reductio
# speedup vs baseline: 1.3614x; 1.0036x over previous
; __device__ __forceinline__ void att_qs(bf16x8 (&pn)[4], f32x16 (&o)[4], f32x16& osum, f32x16& negm, const bf16x8 (&qf)[4], float& m_hat, ...
;     ...
;     kf[0] = ATT_KREAD(0); kf[1] = ATT_KREAD(1); kf[2] = ATT_KREAD(2); kf[3] = ATT_KREAD(3);
;     __builtin_amdgcn_sched_barrier(0);
; #pragma unroll
;     for (int i = 0; i < 8; ++i) {
;         if (i == 0) c0 = __builtin_amdgcn_mfma_f32_32x32x16_bf16(kf[0], qf[0], negm, 0, 0, 0);
;         else if (i == 1) c1 = __builtin_amdgcn_mfma_f32_32x32x16_bf16(kf[1], qf[0], negm, 0, 0, 0);
;         else if ((i & 1) == 0) c0 = __builtin_amdgcn_mfma_f32_32x32x16_bf16(kf[i & 3], qf[i >> 1], c0, 0, 0, 0);
;         else c1 = __builtin_amdgcn_mfma_f32_32x32x16_bf16(kf[i & 3], qf[i >> 1], c1, 0, 0, 0);
;         if (i + 4 < 8) kf[i & 3] = ATT_KREAD(i + 4);
;         __builtin_amdgcn_sched_barrier(0);
;     }
.Latt_fast_entry:
	v_mov_b32_e32 v242, s8
	v_mov_b32_e32 v243, s8
	v_mov_b32_e32 v244, s8
	v_mov_b32_e32 v245, s8
	v_mov_b32_e32 v248, v17
	v_mov_b32_e32 v118, v16
	v_readfirstlane_b32 s98, v178
	v_readfirstlane_b32 s99, v179
	v_readfirstlane_b32 s101, v180
	s_nop 3
	s_sub_u32 s101, s101, s98
	s_mov_b32 s100, 0
	v_mfma_f32_32x32x16_bf16 v[18:33], v[134:137], v[242:245], v[18:33]
	v_mfma_f32_32x32x16_bf16 v[18:33], v[114:117], v[242:245], v[18:33]
	v_mfma_f32_32x32x16_bf16 v[18:33], v[124:127], v[242:245], v[18:33]
	v_mfma_f32_32x32x16_bf16 v[18:33], v[120:123], v[242:245], v[18:33]
	v_mov_b32_e32 v243, 0
	v_mov_b32_e32 v244, 0
	v_mov_b32_e32 v242, 0
	v_mov_b32_e32 v245, 0
	s_add_i32 s10, s57, 0xffff4000
	s_and_b32 s10, s10, 0xc000
	v_add_u32_e32 v133, s10, v185
	s_add_i32 s9, s57, 0xffff8000
	s_and_b32 s9, s9, 0xc000
	v_add_u32_e32 v132, s9, v177
	ds_read_b128 v[128:131], v132
	ds_read_b128 v[138:141], v132 offset:2048
	ds_read_b128 v[142:145], v132 offset:4096
	ds_read_b128 v[250:253], v132 offset:6144
	s_add_i32 s9, s56, 2
	s_min_u32 s9, s9, s52
	s_lshl_b32 s10, s9, 14
	s_mov_b32 s11, 0
	s_add_u32 s10, s98, s10
	s_addc_u32 s11, s99, 0
	s_and_b32 s9, s57, 0xc000
	s_add_i32 s9, s9, s53
	s_mov_b32 m0, s9
	s_nop 0
	global_load_lds_dwordx4 v166, s[10:11]
	s_add_u32 s10, s10, 0x2000
	s_addc_u32 s11, s11, 0
	s_add_i32 m0, s9, 0x2000
	s_nop 0
	global_load_lds_dwordx4 v166, s[10:11]
	s_add_i32 s9, s56, 2
	s_min_u32 s9, s9, s52
	s_lshl_b32 s58, s9, 14
	s_and_b32 s59, s57, 0xc000
	s_add_i32 s59, s59, s53
	s_add_i32 s9, s56, 3
	s_min_u32 s9, s9, s52
	s_lshl_b32 s10, s9, 14
	s_mov_b32 s11, 0
	s_add_u32 s10, s98, s10
	s_addc_u32 s11, s99, 0
	s_add_i32 s9, s57, 0x4000
	s_and_b32 s9, s9, 0xc000
	s_add_i32 s9, s9, s53
	s_waitcnt lgkmcnt(3)
	v_mfma_f32_32x32x16_bf16 v[226:241], v[128:131], v[146:149], v[98:113]
	ds_read_b128 v[128:131], v132 offset:512
	s_waitcnt lgkmcnt(3)
	v_mfma_f32_32x32x16_bf16 v[226:241], v[138:141], v[150:153], v[226:241]
	ds_read_b128 v[138:141], v132 offset:2560
	s_waitcnt lgkmcnt(3)
	v_mfma_f32_32x32x16_bf16 v[226:241], v[142:145], v[154:157], v[226:241]
	ds_read_b128 v[142:145], v132 offset:4608
	s_waitcnt lgkmcnt(3)
	v_mfma_f32_32x32x16_bf16 v[226:241], v[250:253], v[158:161], v[226:241]
	ds_read_b128 v[250:253], v132 offset:6656
	s_waitcnt lgkmcnt(3)
	v_mfma_f32_32x32x16_bf16 v[2:17], v[128:131], v[146:149], v[98:113]
	ds_read_b64_tr_b16 v[128:129], v133
	ds_read_b64_tr_b16 v[130:131], v133 offset:512
	s_waitcnt lgkmcnt(4)
	v_mfma_f32_32x32x16_bf16 v[2:17], v[138:141], v[150:153], v[2:17]
	ds_read_b64_tr_b16 v[138:139], v133 offset:4096
	ds_read_b64_tr_b16 v[140:141], v133 offset:4608
	s_waitcnt lgkmcnt(5)
	v_mfma_f32_32x32x16_bf16 v[2:17], v[142:145], v[154:157], v[2:17]
	ds_read_b64_tr_b16 v[142:143], v133 offset:8192
	ds_read_b64_tr_b16 v[144:145], v133 offset:8704
	s_waitcnt lgkmcnt(6)
	v_mfma_f32_32x32x16_bf16 v[2:17], v[250:253], v[158:161], v[2:17]
	ds_read_b64_tr_b16 v[250:251], v133 offset:12288
	ds_read_b64_tr_b16 v[252:253], v133 offset:12800
	s_branch .Latt_fast_pv

; #define ATT_VREADK(ks) do { _Pragma("unroll") for (int d_ = 0; d_ < 4; ++d_) { vl[(ks) & 1][d_] = vtr(vb + d_ * 4096 + (ks) * 1024); vh[(ks) & 1][d_] = vtr(vb + d_ * 4096 + (ks) * 1024 + 512); } } while (0)
; __device__ __forceinline__ void att_pv(const bf16x8 (&pp)[4], f32x16 (&o)[4], f32x16& osum, const LAS unsigned char* vb) {
;     ...
;     const bf16x8 ones = (bf16x8){0x3F80, 0x3F80, 0x3F80, 0x3F80, 0x3F80, 0x3F80, 0x3F80, 0x3F80};
;     ATT_VREADK(0);
; #pragma unroll
;     for (int ks = 0; ks < 4; ++ks) {
;         if (ks + 1 < 4) ATT_VREADK(ks + 1);
;         osum = __builtin_amdgcn_mfma_f32_32x32x16_bf16(pp[ks], ones, osum, 0, 0, 0);
; #pragma unroll
;         for (int d = 0; d < 4; ++d) { const int bk = ks & 1;
;             const bf16x8 vf = (bf16x8){vl[bk][d][0], vl[bk][d][1], vl[bk][d][2], vl[bk][d][3], vh[bk][d][0], vh[bk][d][1], vh[bk][d][2], vh[bk][d][3]};
;             o[d] = __builtin_amdgcn_mfma_f32_32x32x16_bf16(pp[ks], vf, o[d], 0, 0, 0); }
;     }
.Latt_fast_pv:
	s_waitcnt lgkmcnt(6)
	v_mfma_f32_32x32x16_bf16 v[34:49], v[134:137], v[128:131], v[34:49]
	ds_read_b64_tr_b16 v[128:129], v133 offset:1024
	ds_read_b64_tr_b16 v[130:131], v133 offset:1536
	s_mov_b32 m0, s9
	s_nop 0
	global_load_lds_dwordx4 v166, s[10:11]
	s_waitcnt lgkmcnt(6)
	v_mfma_f32_32x32x16_bf16 v[50:65], v[134:137], v[138:141], v[50:65]
	ds_read_b64_tr_b16 v[138:139], v133 offset:5120
	ds_read_b64_tr_b16 v[140:141], v133 offset:5632
	s_add_u32 s10, s10, 0x2000
	s_addc_u32 s11, s11, 0
	s_add_i32 m0, s9, 0x2000
	s_nop 0
	global_load_lds_dwordx4 v166, s[10:11]
	s_waitcnt lgkmcnt(6)
	v_mfma_f32_32x32x16_bf16 v[66:81], v[134:137], v[142:145], v[66:81]
	ds_read_b64_tr_b16 v[142:143], v133 offset:9216
	ds_read_b64_tr_b16 v[144:145], v133 offset:9728
	s_add_u32 s10, s98, s58
	s_addc_u32 s11, s99, 0
	s_add_u32 s10, s10, s101
	s_addc_u32 s11, s11, 0
	s_add_i32 m0, s59, 0x10000
	s_nop 0
	global_load_lds_dwordx4 v166, s[10:11]
	s_waitcnt lgkmcnt(6)
	v_mfma_f32_32x32x16_bf16 v[82:97], v[134:137], v[250:253], v[82:97]
	ds_read_b64_tr_b16 v[250:251], v133 offset:13312
	ds_read_b64_tr_b16 v[252:253], v133 offset:13824
	s_add_u32 s10, s10, 0x2000
	s_addc_u32 s11, s11, 0
	s_add_i32 m0, s59, 0x12000
	s_nop 0
	global_load_lds_dwordx4 v166, s[10:11]
	s_waitcnt lgkmcnt(6)
	v_mfma_f32_32x32x16_bf16 v[34:49], v[114:117], v[128:131], v[34:49]
	ds_read_b64_tr_b16 v[128:129], v133 offset:2048
	ds_read_b64_tr_b16 v[130:131], v133 offset:2560
	v_max3_f32 v0, v226, v227, v228
	v_max3_f32 v225, v2, v3, v4
	v_max3_f32 v0, v0, v229, v230
	v_max3_f32 v225, v225, v5, v6
	s_waitcnt lgkmcnt(6)
	v_mfma_f32_32x32x16_bf16 v[50:65], v[114:117], v[138:141], v[50:65]
	ds_read_b64_tr_b16 v[138:139], v133 offset:6144
	ds_read_b64_tr_b16 v[140:141], v133 offset:6656
	v_max3_f32 v0, v0, v231, v232
	v_max3_f32 v225, v225, v7, v8
	v_max3_f32 v0, v0, v233, v234
	v_max3_f32 v225, v225, v9, v10
	s_waitcnt lgkmcnt(6)
	v_mfma_f32_32x32x16_bf16 v[66:81], v[114:117], v[142:145], v[66:81]
	ds_read_b64_tr_b16 v[142:143], v133 offset:10240
	ds_read_b64_tr_b16 v[144:145], v133 offset:10752
	v_max3_f32 v0, v0, v235, v236
	v_max3_f32 v225, v225, v11, v12
	v_max3_f32 v0, v0, v237, v238
	v_max3_f32 v225, v225, v13, v14
	s_waitcnt lgkmcnt(6)
	v_mfma_f32_32x32x16_bf16 v[82:97], v[114:117], v[250:253], v[82:97]
	ds_read_b64_tr_b16 v[250:251], v133 offset:14336
	ds_read_b64_tr_b16 v[252:253], v133 offset:14848
	v_max3_f32 v0, v0, v239, v240
	v_max3_f32 v225, v225, v15, v16
	v_max3_f32 v0, v0, v225, v241
	v_max3_f32 v0, v0, v17, v17
	v_cmp_lt_f32_e32 vcc, s36, v0
	s_cbranch_vccnz .Latt_fast_rescale
	s_waitcnt lgkmcnt(6)
	v_mfma_f32_32x32x16_bf16 v[34:49], v[124:127], v[128:131], v[34:49]
	ds_read_b64_tr_b16 v[128:129], v133 offset:3072
	ds_read_b64_tr_b16 v[130:131], v133 offset:3584
	v_exp_f32_e32 v226, v226
	v_exp_f32_e32 v227, v227
	v_add_f32_e32 v243, v243, v226
	v_exp_f32_e32 v228, v228
	v_add_f32_e32 v244, v244, v227
	s_waitcnt lgkmcnt(6)
	v_mfma_f32_32x32x16_bf16 v[50:65], v[124:127], v[138:141], v[50:65]
	ds_read_b64_tr_b16 v[138:139], v133 offset:7168
	ds_read_b64_tr_b16 v[140:141], v133 offset:7680
	v_exp_f32_e32 v229, v229
	v_add_f32_e32 v242, v242, v228
	v_cvt_pk_bf16_f32 v134, v226, v227
	v_add_f32_e32 v245, v245, v229
	v_exp_f32_e32 v230, v230
	s_waitcnt lgkmcnt(6)
	v_mfma_f32_32x32x16_bf16 v[66:81], v[124:127], v[142:145], v[66:81]
	ds_read_b64_tr_b16 v[142:143], v133 offset:11264
	ds_read_b64_tr_b16 v[144:145], v133 offset:11776
	v_exp_f32_e32 v231, v231
	v_add_f32_e32 v243, v243, v230
	v_cvt_pk_bf16_f32 v135, v228, v229
	v_add_f32_e32 v244, v244, v231
	v_exp_f32_e32 v232, v232
	s_waitcnt lgkmcnt(6)
	v_mfma_f32_32x32x16_bf16 v[82:97], v[124:127], v[250:253], v[82:97]
	ds_read_b64_tr_b16 v[250:251], v133 offset:15360
	ds_read_b64_tr_b16 v[252:253], v133 offset:15872
	v_exp_f32_e32 v233, v233
	v_add_f32_e32 v242, v242, v232
	v_cvt_pk_bf16_f32 v136, v230, v231
	v_add_f32_e32 v245, v245, v233
	v_cvt_pk_bf16_f32 v137, v232, v233
	s_waitcnt lgkmcnt(6)
	v_mfma_f32_32x32x16_bf16 v[34:49], v[120:123], v[128:131], v[34:49]
	s_add_i32 s9, s57, 0xffffc000
	s_and_b32 s9, s9, 0xc000
	v_add_u32_e32 v132, s9, v177
	ds_read_b128 v[128:131], v132
	v_exp_f32_e32 v234, v234
	v_exp_f32_e32 v235, v235
	v_add_f32_e32 v243, v243, v234
	v_exp_f32_e32 v236, v236
	v_add_f32_e32 v244, v244, v235
	v_exp_f32_e32 v237, v237
	v_add_f32_e32 v242, v242, v236
	s_waitcnt lgkmcnt(5)
	v_mfma_f32_32x32x16_bf16 v[50:65], v[120:123], v[138:141], v[50:65]
	ds_read_b128 v[138:141], v132 offset:2048
	s_add_i32 s56, s56, 1
	s_addk_i32 s57, 0x4000
	s_add_i32 s55, s55, 64
	s_cmp_lg_u32 s50, s56
	s_cselect_b32 s16, 1, 0
	s_cmp_le_u32 s56, s54
	s_cselect_b32 s16, s16, 0
	s_cmpk_lt_i32 s55, 0xffa6
	s_cselect_b32 s16, s16, 0
	v_cvt_pk_bf16_f32 v114, v234, v235
	v_add_f32_e32 v245, v245, v237
	v_exp_f32_e32 v238, v238
	v_exp_f32_e32 v239, v239
	v_add_f32_e32 v243, v243, v238
	v_cvt_pk_bf16_f32 v115, v236, v237
	v_add_f32_e32 v244, v244, v239
	s_waitcnt lgkmcnt(4)
	v_mfma_f32_32x32x16_bf16 v[66:81], v[120:123], v[142:145], v[66:81]
	ds_read_b128 v[142:145], v132 offset:4096
	v_exp_f32_e32 v240, v240
	v_exp_f32_e32 v241, v241
	v_add_f32_e32 v242, v242, v240
	v_cvt_pk_bf16_f32 v116, v238, v239
	v_add_f32_e32 v245, v245, v241
	v_cvt_pk_bf16_f32 v117, v240, v241
	s_waitcnt lgkmcnt(3)
	v_mfma_f32_32x32x16_bf16 v[82:97], v[120:123], v[250:253], v[82:97]
	ds_read_b128 v[250:253], v132 offset:6144
.Latt_fast_end:
	s_waitcnt vmcnt(4)
	s_barrier
	s_cmp_lg_u32 s16, 0
	s_cbranch_scc0 .Latt_fast_exit
	s_cmp_lg_u32 s100, 0
	s_cbranch_scc1 .Latt_fast_top
	ds_read_b128 v[128:131], v132
	ds_read_b128 v[138:141], v132 offset:2048
	ds_read_b128 v[142:145], v132 offset:4096
	ds_read_b128 v[250:253], v132 offset:6144
	s_mov_b32 s100, 1
	s_branch .Latt_fast_top

; __device__ __forceinline__ unsigned f2bf(float f) { unsigned u = __builtin_bit_cast(unsigned, f); return (u + 0x7fffu + ((u >> 16) & 1u)) >> 16; }
; __device__ __forceinline__ int crow(int r, int hi) { return (r & 3) + 8 * (r >> 2) + 4 * hi; }
; template <int XM> __device__ __forceinline__ float swz_xor(float v) { return __int_as_float(__builtin_amdgcn_ds_swizzle(__float_as_int(v), (XM << 10) | 0x1F)); }
; __device__ __forceinline__ void attn_unit(LAS unsigned char* lds, const bf16_t* Qb, const unsigned char* Kimg, const unsigned char* Vimg, bf16_t* AO, int b, int h, int qpos0, int ntiles, int store_limit, ...
;     ...
;     if (c == 0) {
;         float sg[4];
; #pragma unroll
;         for (int d = 0; d < 4; ++d) sg[d] = subg[32 * d + i32] * post;
; #pragma unroll
;         for (int r = 0; r < 16; ++r) { const int qr = crow(r, hi); float ss = 0.f;
; #pragma unroll
;             for (int d = 0; d < 4; ++d) { o[d][r] += X[qr * 128 + 32 * d + i32]; ss += o[d][r] * o[d][r]; }
;             ss += swz_xor<1>(ss); ss += swz_xor<2>(ss); ss += swz_xor<4>(ss); ss += swz_xor<8>(ss); ss += swz_xor<16>(ss);
;             const float rs = 1.0f / sqrtf(ss * (1.0f / 128.0f) + 1e-5f);
;             const int qp = qp_w + qr;
;             if (qp < store_limit) { bf16_t* op = AO + (rowbase + qp) * DM + h * 128 + i32;
; #pragma unroll
;                 for (int d = 0; d < 4; ++d) op[32 * d] = (bf16_t)f2bf(o[d][r] * rs * sg[d]); } }
.LBB0_715:
	s_andn2_b64 vcc, exec, s[0:1]
	s_waitcnt lgkmcnt(0)
	s_barrier
	s_cbranch_vccnz .LBB0_749
	global_load_dword v9, v[172:173], off
	global_load_dword v46, v[172:173], off offset:128
	global_load_dword v47, v[172:173], off offset:256
	global_load_dword v48, v[172:173], off offset:384
	v_lshl_add_u32 v13, v168, 2, s10
	v_add_u32_e32 v30, v13, v169
	ds_read2_b32 v[10:11], v30 offset1:32
	ds_read2_b32 v[44:45], v30 offset0:64 offset1:96
	s_lshl_b32 s16, s9, 1
	s_waitcnt lgkmcnt(1)
	v_add_f32_e32 v32, v3, v11
	v_add_f32_e32 v33, v0, v10
	v_mul_f32_e32 v0, v32, v32
	s_waitcnt lgkmcnt(0)
	v_add_f32_e32 v31, v8, v44
	v_fmac_f32_e32 v0, v33, v33
	v_add_f32_e32 v30, v2, v45
	v_fmac_f32_e32 v0, v31, v31
	v_fmac_f32_e32 v0, v30, v30
	s_nop 1
	s_waitcnt lgkmcnt(0)
	v_add_f32_dpp v0, v0, v0 quad_perm:[1,0,3,2] row_mask:0xf bank_mask:0xf
	s_nop 1
	s_waitcnt lgkmcnt(0)
	v_add_f32_dpp v0, v0, v0 quad_perm:[2,3,0,1] row_mask:0xf bank_mask:0xf
	s_nop 1
	s_waitcnt lgkmcnt(0)
	v_add_f32_dpp v8, v0, v0 row_half_mirror row_mask:0xf bank_mask:0xf
	s_nop 1
	v_add_u32_e32 v0, s46, v186
	v_lshl_add_u64 v[2:3], v[174:175], 0, s[16:17]
	v_cmp_gt_u32_e32 vcc, s44, v0
	s_waitcnt lgkmcnt(0)
	v_add_f32_dpp v43, v8, v8 row_mirror row_mask:0xf bank_mask:0xf
	ds_swizzle_b32 v44, v43 offset:swizzle(SWAP,16)
	s_waitcnt vmcnt(3)
	v_mul_f32_e32 v11, 0x3f24fd5c, v9
	s_waitcnt vmcnt(2)
	v_mul_f32_e32 v10, 0x3f24fd5c, v46
	s_waitcnt vmcnt(1)
	v_mul_f32_e32 v9, 0x3f24fd5c, v47
	s_waitcnt vmcnt(0)
	v_mul_f32_e32 v8, 0x3f24fd5c, v48
	s_and_saveexec_b64 s[10:11], vcc
	s_cbranch_execz .LBB0_718
	s_waitcnt lgkmcnt(0)
	v_add_f32_e32 v43, v43, v44
	v_fmamk_f32 v43, v43, 0x3c000000, v220
	v_mul_f32_e32 v44, 0x4f800000, v43
	v_cmp_gt_f32_e32 vcc, s39, v43
	v_add_u32_e32 v0, s45, v0
	s_nop 0
	v_cndmask_b32_e32 v43, v43, v44, vcc
	v_sqrt_f32_e32 v44, v43
	s_nop 0
	v_add_u32_e32 v45, -1, v44
	v_fma_f32 v47, -v45, v44, v43
	v_add_u32_e32 v46, 1, v44
	v_cmp_ge_f32_e64 s[0:1], 0, v47
	s_nop 1
	v_cndmask_b32_e64 v45, v44, v45, s[0:1]
	v_fma_f32 v44, -v46, v44, v43
	v_cmp_lt_f32_e64 s[0:1], 0, v44
	s_nop 1
	v_cndmask_b32_e64 v44, v45, v46, s[0:1]
	v_mul_f32_e32 v45, 0x37800000, v44
	v_cndmask_b32_e32 v44, v44, v45, vcc
	v_cmp_class_f32_e32 vcc, v43, v221
	s_nop 1
	v_cndmask_b32_e32 v43, v44, v43, vcc
	v_div_scale_f32 v44, s[0:1], v43, v43, 1.0
	v_rcp_f32_e32 v45, v44
	s_nop 0
	v_fma_f32 v46, -v44, v45, 1.0
	v_fmac_f32_e32 v45, v46, v45
	v_div_scale_f32 v46, vcc, 1.0, v43, 1.0
	v_mul_f32_e32 v47, v46, v45
	v_fma_f32 v48, -v44, v47, v46
	v_fmac_f32_e32 v47, v48, v45
	v_fma_f32 v44, -v44, v47, v46
	v_div_fmas_f32 v44, v44, v45, v47
	v_div_fixup_f32 v43, v44, v43, 1.0
	v_lshlrev_b64 v[44:45], 11, v[0:1]
	v_mul_f32_e32 v0, v33, v43
	v_mul_f32_e32 v0, v11, v0
	v_bfe_u32 v33, v0, 16, 1
	v_lshl_add_u64 v[44:45], v[2:3], 0, v[44:45]
	v_add3_u32 v0, v0, v33, s40
	global_store_short_d16_hi v[44:45], v0, off
	v_mul_f32_e32 v0, v32, v43
	v_mul_f32_e32 v0, v10, v0
	v_bfe_u32 v32, v0, 16, 1
	v_add3_u32 v0, v0, v32, s40
	global_store_short_d16_hi v[44:45], v0, off offset:64
	v_mul_f32_e32 v0, v31, v43
	v_mul_f32_e32 v0, v9, v0
	v_bfe_u32 v31, v0, 16, 1
	v_add3_u32 v0, v0, v31, s40
	global_store_short_d16_hi v[44:45], v0, off offset:128
	v_mul_f32_e32 v0, v30, v43
	v_mul_f32_e32 v0, v8, v0
	v_bfe_u32 v30, v0, 16, 1
	v_add3_u32 v0, v0, v30, s40
	global_store_short_d16_hi v[44:45], v0, off offset:192
.LBB0_718:
	s_or_b64 exec, exec, s[10:11]
	v_add_u32_e32 v0, v13, v189
	ds_read2_b32 v[30:31], v0 offset1:32
	s_waitcnt lgkmcnt(1)
	ds_read2_b32 v[44:45], v0 offset0:64 offset1:96
	s_waitcnt lgkmcnt(1)
	v_add_f32_e32 v32, v110, v31
	v_add_f32_e32 v33, v108, v30
	v_mul_f32_e32 v0, v32, v32
	s_waitcnt lgkmcnt(0)
	v_add_f32_e32 v30, v111, v44
	v_fmac_f32_e32 v0, v33, v33
	v_fmac_f32_e32 v0, v30, v30
	v_add_f32_e32 v31, v109, v45
	v_fmac_f32_e32 v0, v31, v31
	s_nop 1
	s_waitcnt lgkmcnt(0)
	v_add_f32_dpp v0, v0, v0 quad_perm:[1,0,3,2] row_mask:0xf bank_mask:0xf
	s_nop 1
	s_waitcnt lgkmcnt(0)
	v_add_f32_dpp v0, v0, v0 quad_perm:[2,3,0,1] row_mask:0xf bank_mask:0xf
	s_nop 1
	s_waitcnt lgkmcnt(0)
	v_add_f32_dpp v0, v0, v0 row_half_mirror row_mask:0xf bank_mask:0xf
	s_nop 1
	s_waitcnt lgkmcnt(0)
	v_add_f32_dpp v43, v0, v0 row_mirror row_mask:0xf bank_mask:0xf
	ds_swizzle_b32 v44, v43 offset:swizzle(SWAP,16)
	v_add_u32_e32 v0, s46, v171
	v_cmp_gt_u32_e32 vcc, s44, v0
	s_and_saveexec_b64 s[10:11], vcc
	s_cbranch_execz .LBB0_720
	s_waitcnt lgkmcnt(0)
	v_add_f32_e32 v43, v43, v44
	v_fmamk_f32 v43, v43, 0x3c000000, v220
	v_mul_f32_e32 v44, 0x4f800000, v43
	v_cmp_gt_f32_e32 vcc, s39, v43
	v_add_u32_e32 v0, s45, v0
	s_nop 0
	v_cndmask_b32_e32 v43, v43, v44, vcc
	v_sqrt_f32_e32 v44, v43
	s_nop 0
	v_add_u32_e32 v45, -1, v44
	v_fma_f32 v47, -v45, v44, v43
	v_add_u32_e32 v46, 1, v44
	v_cmp_ge_f32_e64 s[0:1], 0, v47
	s_nop 1
	v_cndmask_b32_e64 v45, v44, v45, s[0:1]
	v_fma_f32 v44, -v46, v44, v43
	v_cmp_lt_f32_e64 s[0:1], 0, v44
	s_nop 1
	v_cndmask_b32_e64 v44, v45, v46, s[0:1]
	v_mul_f32_e32 v45, 0x37800000, v44
	v_cndmask_b32_e32 v44, v44, v45, vcc
	v_cmp_class_f32_e32 vcc, v43, v221
	s_nop 1
	v_cndmask_b32_e32 v43, v44, v43, vcc
	v_div_scale_f32 v44, s[0:1], v43, v43, 1.0
	v_rcp_f32_e32 v45, v44
	s_nop 0
	v_fma_f32 v46, -v44, v45, 1.0
	v_fmac_f32_e32 v45, v46, v45
	v_div_scale_f32 v46, vcc, 1.0, v43, 1.0
	v_mul_f32_e32 v47, v46, v45
	v_fma_f32 v48, -v44, v47, v46
	v_fmac_f32_e32 v47, v48, v45
	v_fma_f32 v44, -v44, v47, v46
	v_div_fmas_f32 v44, v44, v45, v47
	v_div_fixup_f32 v43, v44, v43, 1.0
	v_lshlrev_b64 v[44:45], 11, v[0:1]
	v_mul_f32_e32 v0, v33, v43
	v_mul_f32_e32 v0, v11, v0
	v_bfe_u32 v33, v0, 16, 1
	v_lshl_add_u64 v[44:45], v[2:3], 0, v[44:45]
	v_add3_u32 v0, v0, v33, s40
	global_store_short_d16_hi v[44:45], v0, off
	v_mul_f32_e32 v0, v32, v43
	v_mul_f32_e32 v0, v10, v0
	v_bfe_u32 v32, v0, 16, 1
	v_add3_u32 v0, v0, v32, s40
	global_store_short_d16_hi v[44:45], v0, off offset:64
	v_mul_f32_e32 v0, v30, v43
	v_mul_f32_e32 v0, v9, v0
	v_bfe_u32 v30, v0, 16, 1
	v_add3_u32 v0, v0, v30, s40
	global_store_short_d16_hi v[44:45], v0, off offset:128
	v_mul_f32_e32 v0, v31, v43
	v_mul_f32_e32 v0, v8, v0
	v_bfe_u32 v30, v0, 16, 1
	v_add3_u32 v0, v0, v30, s40
	global_store_short_d16_hi v[44:45], v0, off offset:192
; __device__ __forceinline__ unsigned f2bf(float f) { unsigned u = __builtin_bit_cast(unsigned, f); return (u + 0x7fffu + ((u >> 16) & 1u)) >> 16; }
; __device__ __forceinline__ int crow(int r, int hi) { return (r & 3) + 8 * (r >> 2) + 4 * hi; }
; template <int XM> __device__ __forceinline__ float swz_xor(float v) { return __int_as_float(__builtin_amdgcn_ds_swizzle(__float_as_int(v), (XM << 10) | 0x1F)); }
; __device__ __forceinline__ void attn_unit(LAS unsigned char* lds, const bf16_t* Qb, const unsigned char* Kimg, const unsigned char* Vimg, bf16_t* AO, int b, int h, int qpos0, int ntiles, int store_limit, ...
;     ...
;         for (int r = 0; r < 16; ++r) { const int qr = crow(r, hi); float ss = 0.f;
; #pragma unroll
;             for (int d = 0; d < 4; ++d) { o[d][r] += X[qr * 128 + 32 * d + i32]; ss += o[d][r] * o[d][r]; }
;             ss += swz_xor<1>(ss); ss += swz_xor<2>(ss); ss += swz_xor<4>(ss); ss += swz_xor<8>(ss); ss += swz_xor<16>(ss);
;             const float rs = 1.0f / sqrtf(ss * (1.0f / 128.0f) + 1e-5f);
;             const int qp = qp_w + qr;
;             if (qp < store_limit) { bf16_t* op = AO + (rowbase + qp) * DM + h * 128 + i32;
; #pragma unroll
;                 for (int d = 0; d < 4; ++d) op[32 * d] = (bf16_t)f2bf(o[d][r] * rs * sg[d]); } }
.LBB0_720:
	s_or_b64 exec, exec, s[10:11]
	v_add_u32_e32 v0, v13, v191
	ds_read2_b32 v[30:31], v0 offset1:32
	s_waitcnt lgkmcnt(1)
	ds_read2_b32 v[44:45], v0 offset0:64 offset1:96
	s_waitcnt lgkmcnt(1)
	v_add_f32_e32 v32, v106, v31
	v_add_f32_e32 v33, v104, v30
	v_mul_f32_e32 v0, v32, v32
	s_waitcnt lgkmcnt(0)
	v_add_f32_e32 v30, v107, v44
	v_fmac_f32_e32 v0, v33, v33
	v_fmac_f32_e32 v0, v30, v30
	v_add_f32_e32 v31, v105, v45
	v_fmac_f32_e32 v0, v31, v31
	s_nop 1
	s_waitcnt lgkmcnt(0)
	v_add_f32_dpp v0, v0, v0 quad_perm:[1,0,3,2] row_mask:0xf bank_mask:0xf
	s_nop 1
	s_waitcnt lgkmcnt(0)
	v_add_f32_dpp v0, v0, v0 quad_perm:[2,3,0,1] row_mask:0xf bank_mask:0xf
	s_nop 1
	s_waitcnt lgkmcnt(0)
	v_add_f32_dpp v0, v0, v0 row_half_mirror row_mask:0xf bank_mask:0xf
	s_nop 1
	s_waitcnt lgkmcnt(0)
	v_add_f32_dpp v43, v0, v0 row_mirror row_mask:0xf bank_mask:0xf
	ds_swizzle_b32 v44, v43 offset:swizzle(SWAP,16)
	v_add_u32_e32 v0, s46, v190
	v_cmp_gt_u32_e32 vcc, s44, v0
	s_and_saveexec_b64 s[10:11], vcc
	s_cbranch_execz .LBB0_722
	s_waitcnt lgkmcnt(0)
	v_add_f32_e32 v43, v43, v44
	v_fmamk_f32 v43, v43, 0x3c000000, v220
	v_mul_f32_e32 v44, 0x4f800000, v43
	v_cmp_gt_f32_e32 vcc, s39, v43
	v_add_u32_e32 v0, s45, v0
	s_nop 0
	v_cndmask_b32_e32 v43, v43, v44, vcc
	v_sqrt_f32_e32 v44, v43
	s_nop 0
	v_add_u32_e32 v45, -1, v44
	v_fma_f32 v47, -v45, v44, v43
	v_add_u32_e32 v46, 1, v44
	v_cmp_ge_f32_e64 s[0:1], 0, v47
	s_nop 1
	v_cndmask_b32_e64 v45, v44, v45, s[0:1]
	v_fma_f32 v44, -v46, v44, v43
	v_cmp_lt_f32_e64 s[0:1], 0, v44
	s_nop 1
	v_cndmask_b32_e64 v44, v45, v46, s[0:1]
	v_mul_f32_e32 v45, 0x37800000, v44
	v_cndmask_b32_e32 v44, v44, v45, vcc
	v_cmp_class_f32_e32 vcc, v43, v221
	s_nop 1
	v_cndmask_b32_e32 v43, v44, v43, vcc
	v_div_scale_f32 v44, s[0:1], v43, v43, 1.0
	v_rcp_f32_e32 v45, v44
	s_nop 0
	v_fma_f32 v46, -v44, v45, 1.0
	v_fmac_f32_e32 v45, v46, v45
	v_div_scale_f32 v46, vcc, 1.0, v43, 1.0
	v_mul_f32_e32 v47, v46, v45
	v_fma_f32 v48, -v44, v47, v46
	v_fmac_f32_e32 v47, v48, v45
	v_fma_f32 v44, -v44, v47, v46
	v_div_fmas_f32 v44, v44, v45, v47
	v_div_fixup_f32 v43, v44, v43, 1.0
	v_lshlrev_b64 v[44:45], 11, v[0:1]
	v_mul_f32_e32 v0, v33, v43
	v_mul_f32_e32 v0, v11, v0
	v_bfe_u32 v33, v0, 16, 1
	v_lshl_add_u64 v[44:45], v[2:3], 0, v[44:45]
	v_add3_u32 v0, v0, v33, s40
	global_store_short_d16_hi v[44:45], v0, off
	v_mul_f32_e32 v0, v32, v43
	v_mul_f32_e32 v0, v10, v0
	v_bfe_u32 v32, v0, 16, 1
	v_add3_u32 v0, v0, v32, s40
	global_store_short_d16_hi v[44:45], v0, off offset:64
	v_mul_f32_e32 v0, v30, v43
	v_mul_f32_e32 v0, v9, v0
	v_bfe_u32 v30, v0, 16, 1
	v_add3_u32 v0, v0, v30, s40
	global_store_short_d16_hi v[44:45], v0, off offset:128
	v_mul_f32_e32 v0, v31, v43
	v_mul_f32_e32 v0, v8, v0
	v_bfe_u32 v30, v0, 16, 1
	v_add3_u32 v0, v0, v30, s40
	global_store_short_d16_hi v[44:45], v0, off offset:192
.LBB0_722:
	s_or_b64 exec, exec, s[10:11]
	v_add_u32_e32 v0, v13, v193
	ds_read2_b32 v[30:31], v0 offset1:32
	s_waitcnt lgkmcnt(1)
	ds_read2_b32 v[44:45], v0 offset0:64 offset1:96
	s_waitcnt lgkmcnt(1)
	v_add_f32_e32 v32, v102, v31
	v_add_f32_e32 v33, v100, v30
	v_mul_f32_e32 v0, v32, v32
	s_waitcnt lgkmcnt(0)
	v_add_f32_e32 v30, v103, v44
	v_fmac_f32_e32 v0, v33, v33
	v_fmac_f32_e32 v0, v30, v30
	v_add_f32_e32 v31, v101, v45
	v_fmac_f32_e32 v0, v31, v31
	s_nop 1
	s_waitcnt lgkmcnt(0)
	v_add_f32_dpp v0, v0, v0 quad_perm:[1,0,3,2] row_mask:0xf bank_mask:0xf
	s_nop 1
	s_waitcnt lgkmcnt(0)
	v_add_f32_dpp v0, v0, v0 quad_perm:[2,3,0,1] row_mask:0xf bank_mask:0xf
	s_nop 1
	s_waitcnt lgkmcnt(0)
	v_add_f32_dpp v0, v0, v0 row_half_mirror row_mask:0xf bank_mask:0xf
	s_nop 1
	s_waitcnt lgkmcnt(0)
	v_add_f32_dpp v43, v0, v0 row_mirror row_mask:0xf bank_mask:0xf
	ds_swizzle_b32 v44, v43 offset:swizzle(SWAP,16)
	v_add_u32_e32 v0, s46, v192
	v_cmp_gt_u32_e32 vcc, s44, v0
	s_and_saveexec_b64 s[10:11], vcc
	s_cbranch_execz .LBB0_724
	s_waitcnt lgkmcnt(0)
	v_add_f32_e32 v43, v43, v44
	v_fmamk_f32 v43, v43, 0x3c000000, v220
	v_mul_f32_e32 v44, 0x4f800000, v43
	v_cmp_gt_f32_e32 vcc, s39, v43
	v_add_u32_e32 v0, s45, v0
	s_nop 0
	v_cndmask_b32_e32 v43, v43, v44, vcc
	v_sqrt_f32_e32 v44, v43
	s_nop 0
	v_add_u32_e32 v45, -1, v44
	v_fma_f32 v47, -v45, v44, v43
	v_add_u32_e32 v46, 1, v44
	v_cmp_ge_f32_e64 s[0:1], 0, v47
	s_nop 1
	v_cndmask_b32_e64 v45, v44, v45, s[0:1]
	v_fma_f32 v44, -v46, v44, v43
	v_cmp_lt_f32_e64 s[0:1], 0, v44
	s_nop 1
	v_cndmask_b32_e64 v44, v45, v46, s[0:1]
	v_mul_f32_e32 v45, 0x37800000, v44
	v_cndmask_b32_e32 v44, v44, v45, vcc
	v_cmp_class_f32_e32 vcc, v43, v221
	s_nop 1
	v_cndmask_b32_e32 v43, v44, v43, vcc
	v_div_scale_f32 v44, s[0:1], v43, v43, 1.0
	v_rcp_f32_e32 v45, v44
	s_nop 0
	v_fma_f32 v46, -v44, v45, 1.0
	v_fmac_f32_e32 v45, v46, v45
	v_div_scale_f32 v46, vcc, 1.0, v43, 1.0
	v_mul_f32_e32 v47, v46, v45
	v_fma_f32 v48, -v44, v47, v46
	v_fmac_f32_e32 v47, v48, v45
	v_fma_f32 v44, -v44, v47, v46
	v_div_fmas_f32 v44, v44, v45, v47
	v_div_fixup_f32 v43, v44, v43, 1.0
	v_lshlrev_b64 v[44:45], 11, v[0:1]
	v_mul_f32_e32 v0, v33, v43
	v_mul_f32_e32 v0, v11, v0
	v_bfe_u32 v33, v0, 16, 1
	v_lshl_add_u64 v[44:45], v[2:3], 0, v[44:45]
	v_add3_u32 v0, v0, v33, s40
	global_store_short_d16_hi v[44:45], v0, off
	v_mul_f32_e32 v0, v32, v43
	v_mul_f32_e32 v0, v10, v0
	v_bfe_u32 v32, v0, 16, 1
	v_add3_u32 v0, v0, v32, s40
	global_store_short_d16_hi v[44:45], v0, off offset:64
	v_mul_f32_e32 v0, v30, v43
	v_mul_f32_e32 v0, v9, v0
	v_bfe_u32 v30, v0, 16, 1
	v_add3_u32 v0, v0, v30, s40
	global_store_short_d16_hi v[44:45], v0, off offset:128
	v_mul_f32_e32 v0, v31, v43
	v_mul_f32_e32 v0, v8, v0
	v_bfe_u32 v30, v0, 16, 1
	v_add3_u32 v0, v0, v30, s40
	global_store_short_d16_hi v[44:45], v0, off offset:192
; __device__ __forceinline__ unsigned f2bf(float f) { unsigned u = __builtin_bit_cast(unsigned, f); return (u + 0x7fffu + ((u >> 16) & 1u)) >> 16; }
; __device__ __forceinline__ int crow(int r, int hi) { return (r & 3) + 8 * (r >> 2) + 4 * hi; }
; template <int XM> __device__ __forceinline__ float swz_xor(float v) { return __int_as_float(__builtin_amdgcn_ds_swizzle(__float_as_int(v), (XM << 10) | 0x1F)); }
; __device__ __forceinline__ void attn_unit(LAS unsigned char* lds, const bf16_t* Qb, const unsigned char* Kimg, const unsigned char* Vimg, bf16_t* AO, int b, int h, int qpos0, int ntiles, int store_limit, ...
;     ...
;         for (int r = 0; r < 16; ++r) { const int qr = crow(r, hi); float ss = 0.f;
; #pragma unroll
;             for (int d = 0; d < 4; ++d) { o[d][r] += X[qr * 128 + 32 * d + i32]; ss += o[d][r] * o[d][r]; }
;             ss += swz_xor<1>(ss); ss += swz_xor<2>(ss); ss += swz_xor<4>(ss); ss += swz_xor<8>(ss); ss += swz_xor<16>(ss);
;             const float rs = 1.0f / sqrtf(ss * (1.0f / 128.0f) + 1e-5f);
;             const int qp = qp_w + qr;
;             if (qp < store_limit) { bf16_t* op = AO + (rowbase + qp) * DM + h * 128 + i32;
; #pragma unroll
;                 for (int d = 0; d < 4; ++d) op[32 * d] = (bf16_t)f2bf(o[d][r] * rs * sg[d]); } }
.LBB0_724:
	s_or_b64 exec, exec, s[10:11]
	v_add_u32_e32 v0, v13, v195
	ds_read2_b32 v[30:31], v0 offset1:32
	s_waitcnt lgkmcnt(1)
	ds_read2_b32 v[44:45], v0 offset0:64 offset1:96
	s_waitcnt lgkmcnt(1)
	v_add_f32_e32 v32, v98, v31
	v_add_f32_e32 v33, v84, v30
	v_mul_f32_e32 v0, v32, v32
	s_waitcnt lgkmcnt(0)
	v_add_f32_e32 v30, v99, v44
	v_fmac_f32_e32 v0, v33, v33
	v_fmac_f32_e32 v0, v30, v30
	v_add_f32_e32 v31, v85, v45
	v_fmac_f32_e32 v0, v31, v31
	s_nop 1
	s_waitcnt lgkmcnt(0)
	v_add_f32_dpp v0, v0, v0 quad_perm:[1,0,3,2] row_mask:0xf bank_mask:0xf
	s_nop 1
	s_waitcnt lgkmcnt(0)
	v_add_f32_dpp v0, v0, v0 quad_perm:[2,3,0,1] row_mask:0xf bank_mask:0xf
	s_nop 1
	s_waitcnt lgkmcnt(0)
	v_add_f32_dpp v0, v0, v0 row_half_mirror row_mask:0xf bank_mask:0xf
	s_nop 1
	s_waitcnt lgkmcnt(0)
	v_add_f32_dpp v43, v0, v0 row_mirror row_mask:0xf bank_mask:0xf
	ds_swizzle_b32 v44, v43 offset:swizzle(SWAP,16)
	v_add_u32_e32 v0, s46, v194
	v_cmp_gt_u32_e32 vcc, s44, v0
	s_and_saveexec_b64 s[10:11], vcc
	s_cbranch_execz .LBB0_726
	s_waitcnt lgkmcnt(0)
	v_add_f32_e32 v43, v43, v44
	v_fmamk_f32 v43, v43, 0x3c000000, v220
	v_mul_f32_e32 v44, 0x4f800000, v43
	v_cmp_gt_f32_e32 vcc, s39, v43
	v_add_u32_e32 v0, s45, v0
	s_nop 0
	v_cndmask_b32_e32 v43, v43, v44, vcc
	v_sqrt_f32_e32 v44, v43
	s_nop 0
	v_add_u32_e32 v45, -1, v44
	v_fma_f32 v47, -v45, v44, v43
	v_add_u32_e32 v46, 1, v44
	v_cmp_ge_f32_e64 s[0:1], 0, v47
	s_nop 1
	v_cndmask_b32_e64 v45, v44, v45, s[0:1]
	v_fma_f32 v44, -v46, v44, v43
	v_cmp_lt_f32_e64 s[0:1], 0, v44
	s_nop 1
	v_cndmask_b32_e64 v44, v45, v46, s[0:1]
	v_mul_f32_e32 v45, 0x37800000, v44
	v_cndmask_b32_e32 v44, v44, v45, vcc
	v_cmp_class_f32_e32 vcc, v43, v221
	s_nop 1
	v_cndmask_b32_e32 v43, v44, v43, vcc
	v_div_scale_f32 v44, s[0:1], v43, v43, 1.0
	v_rcp_f32_e32 v45, v44
	s_nop 0
	v_fma_f32 v46, -v44, v45, 1.0
	v_fmac_f32_e32 v45, v46, v45
	v_div_scale_f32 v46, vcc, 1.0, v43, 1.0
	v_mul_f32_e32 v47, v46, v45
	v_fma_f32 v48, -v44, v47, v46
	v_fmac_f32_e32 v47, v48, v45
	v_fma_f32 v44, -v44, v47, v46
	v_div_fmas_f32 v44, v44, v45, v47
	v_div_fixup_f32 v43, v44, v43, 1.0
	v_lshlrev_b64 v[44:45], 11, v[0:1]
	v_mul_f32_e32 v0, v33, v43
	v_mul_f32_e32 v0, v11, v0
	v_bfe_u32 v33, v0, 16, 1
	v_lshl_add_u64 v[44:45], v[2:3], 0, v[44:45]
	v_add3_u32 v0, v0, v33, s40
	global_store_short_d16_hi v[44:45], v0, off
	v_mul_f32_e32 v0, v32, v43
	v_mul_f32_e32 v0, v10, v0
	v_bfe_u32 v32, v0, 16, 1
	v_add3_u32 v0, v0, v32, s40
	global_store_short_d16_hi v[44:45], v0, off offset:64
	v_mul_f32_e32 v0, v30, v43
	v_mul_f32_e32 v0, v9, v0
	v_bfe_u32 v30, v0, 16, 1
	v_add3_u32 v0, v0, v30, s40
	global_store_short_d16_hi v[44:45], v0, off offset:128
	v_mul_f32_e32 v0, v31, v43
	v_mul_f32_e32 v0, v8, v0
	v_bfe_u32 v30, v0, 16, 1
	v_add3_u32 v0, v0, v30, s40
	global_store_short_d16_hi v[44:45], v0, off offset:192
.LBB0_726:
	s_or_b64 exec, exec, s[10:11]
	v_add_u32_e32 v0, v13, v197
	ds_read2_b32 v[30:31], v0 offset1:32
	s_waitcnt lgkmcnt(1)
	ds_read2_b32 v[44:45], v0 offset0:64 offset1:96
	s_waitcnt lgkmcnt(1)
	v_add_f32_e32 v32, v82, v31
	v_add_f32_e32 v33, v70, v30
	v_mul_f32_e32 v0, v32, v32
	s_waitcnt lgkmcnt(0)
	v_add_f32_e32 v30, v83, v44
	v_fmac_f32_e32 v0, v33, v33
	v_fmac_f32_e32 v0, v30, v30
	v_add_f32_e32 v31, v71, v45
	v_fmac_f32_e32 v0, v31, v31
	s_nop 1
	s_waitcnt lgkmcnt(0)
	v_add_f32_dpp v0, v0, v0 quad_perm:[1,0,3,2] row_mask:0xf bank_mask:0xf
	s_nop 1
	s_waitcnt lgkmcnt(0)
	v_add_f32_dpp v0, v0, v0 quad_perm:[2,3,0,1] row_mask:0xf bank_mask:0xf
	s_nop 1
	s_waitcnt lgkmcnt(0)
	v_add_f32_dpp v0, v0, v0 row_half_mirror row_mask:0xf bank_mask:0xf
	s_nop 1
	s_waitcnt lgkmcnt(0)
	v_add_f32_dpp v43, v0, v0 row_mirror row_mask:0xf bank_mask:0xf
	ds_swizzle_b32 v44, v43 offset:swizzle(SWAP,16)
	v_add_u32_e32 v0, s46, v196
	v_cmp_gt_u32_e32 vcc, s44, v0
	s_and_saveexec_b64 s[10:11], vcc
	s_cbranch_execz .LBB0_728
	s_waitcnt lgkmcnt(0)
	v_add_f32_e32 v43, v43, v44
	v_fmamk_f32 v43, v43, 0x3c000000, v220
	v_mul_f32_e32 v44, 0x4f800000, v43
	v_cmp_gt_f32_e32 vcc, s39, v43
	v_add_u32_e32 v0, s45, v0
	s_nop 0
	v_cndmask_b32_e32 v43, v43, v44, vcc
	v_sqrt_f32_e32 v44, v43
	s_nop 0
	v_add_u32_e32 v45, -1, v44
	v_fma_f32 v47, -v45, v44, v43
	v_add_u32_e32 v46, 1, v44
	v_cmp_ge_f32_e64 s[0:1], 0, v47
	s_nop 1
	v_cndmask_b32_e64 v45, v44, v45, s[0:1]
	v_fma_f32 v44, -v46, v44, v43
	v_cmp_lt_f32_e64 s[0:1], 0, v44
	s_nop 1
	v_cndmask_b32_e64 v44, v45, v46, s[0:1]
	v_mul_f32_e32 v45, 0x37800000, v44
	v_cndmask_b32_e32 v44, v44, v45, vcc
	v_cmp_class_f32_e32 vcc, v43, v221
	s_nop 1
	v_cndmask_b32_e32 v43, v44, v43, vcc
	v_div_scale_f32 v44, s[0:1], v43, v43, 1.0
	v_rcp_f32_e32 v45, v44
	s_nop 0
	v_fma_f32 v46, -v44, v45, 1.0
	v_fmac_f32_e32 v45, v46, v45
	v_div_scale_f32 v46, vcc, 1.0, v43, 1.0
	v_mul_f32_e32 v47, v46, v45
	v_fma_f32 v48, -v44, v47, v46
	v_fmac_f32_e32 v47, v48, v45
	v_fma_f32 v44, -v44, v47, v46
	v_div_fmas_f32 v44, v44, v45, v47
	v_div_fixup_f32 v43, v44, v43, 1.0
	v_lshlrev_b64 v[44:45], 11, v[0:1]
	v_mul_f32_e32 v0, v33, v43
	v_mul_f32_e32 v0, v11, v0
	v_bfe_u32 v33, v0, 16, 1
	v_lshl_add_u64 v[44:45], v[2:3], 0, v[44:45]
	v_add3_u32 v0, v0, v33, s40
	global_store_short_d16_hi v[44:45], v0, off
	v_mul_f32_e32 v0, v32, v43
	v_mul_f32_e32 v0, v10, v0
	v_bfe_u32 v32, v0, 16, 1
	v_add3_u32 v0, v0, v32, s40
	global_store_short_d16_hi v[44:45], v0, off offset:64
	v_mul_f32_e32 v0, v30, v43
	v_mul_f32_e32 v0, v9, v0
	v_bfe_u32 v30, v0, 16, 1
	v_add3_u32 v0, v0, v30, s40
	global_store_short_d16_hi v[44:45], v0, off offset:128
	v_mul_f32_e32 v0, v31, v43
	v_mul_f32_e32 v0, v8, v0
	v_bfe_u32 v30, v0, 16, 1
	v_add3_u32 v0, v0, v30, s40
	global_store_short_d16_hi v[44:45], v0, off offset:192
; __device__ __forceinline__ unsigned f2bf(float f) { unsigned u = __builtin_bit_cast(unsigned, f); return (u + 0x7fffu + ((u >> 16) & 1u)) >> 16; }
; __device__ __forceinline__ int crow(int r, int hi) { return (r & 3) + 8 * (r >> 2) + 4 * hi; }
; template <int XM> __device__ __forceinline__ float swz_xor(float v) { return __int_as_float(__builtin_amdgcn_ds_swizzle(__float_as_int(v), (XM << 10) | 0x1F)); }
; __device__ __forceinline__ void attn_unit(LAS unsigned char* lds, const bf16_t* Qb, const unsigned char* Kimg, const unsigned char* Vimg, bf16_t* AO, int b, int h, int qpos0, int ntiles, int store_limit, ...
;     ...
;         for (int r = 0; r < 16; ++r) { const int qr = crow(r, hi); float ss = 0.f;
; #pragma unroll
;             for (int d = 0; d < 4; ++d) { o[d][r] += X[qr * 128 + 32 * d + i32]; ss += o[d][r] * o[d][r]; }
;             ss += swz_xor<1>(ss); ss += swz_xor<2>(ss); ss += swz_xor<4>(ss); ss += swz_xor<8>(ss); ss += swz_xor<16>(ss);
;             const float rs = 1.0f / sqrtf(ss * (1.0f / 128.0f) + 1e-5f);
;             const int qp = qp_w + qr;
;             if (qp < store_limit) { bf16_t* op = AO + (rowbase + qp) * DM + h * 128 + i32;
; #pragma unroll
;                 for (int d = 0; d < 4; ++d) op[32 * d] = (bf16_t)f2bf(o[d][r] * rs * sg[d]); } }
.LBB0_728:
	s_or_b64 exec, exec, s[10:11]
	v_add_u32_e32 v0, v13, v199
	ds_read2_b32 v[30:31], v0 offset1:32
	s_waitcnt lgkmcnt(1)
	ds_read2_b32 v[44:45], v0 offset0:64 offset1:96
	s_waitcnt lgkmcnt(1)
	v_add_f32_e32 v32, v68, v31
	v_add_f32_e32 v33, v66, v30
	v_mul_f32_e32 v0, v32, v32
	s_waitcnt lgkmcnt(0)
	v_add_f32_e32 v30, v69, v44
	v_fmac_f32_e32 v0, v33, v33
	v_fmac_f32_e32 v0, v30, v30
	v_add_f32_e32 v31, v67, v45
	v_fmac_f32_e32 v0, v31, v31
	s_nop 1
	s_waitcnt lgkmcnt(0)
	v_add_f32_dpp v0, v0, v0 quad_perm:[1,0,3,2] row_mask:0xf bank_mask:0xf
	s_nop 1
	s_waitcnt lgkmcnt(0)
	v_add_f32_dpp v0, v0, v0 quad_perm:[2,3,0,1] row_mask:0xf bank_mask:0xf
	s_nop 1
	s_waitcnt lgkmcnt(0)
	v_add_f32_dpp v0, v0, v0 row_half_mirror row_mask:0xf bank_mask:0xf
	s_nop 1
	s_waitcnt lgkmcnt(0)
	v_add_f32_dpp v43, v0, v0 row_mirror row_mask:0xf bank_mask:0xf
	ds_swizzle_b32 v44, v43 offset:swizzle(SWAP,16)
	v_add_u32_e32 v0, s46, v198
	v_cmp_gt_u32_e32 vcc, s44, v0
	s_and_saveexec_b64 s[10:11], vcc
	s_cbranch_execz .LBB0_730
	s_waitcnt lgkmcnt(0)
	v_add_f32_e32 v43, v43, v44
	v_fmamk_f32 v43, v43, 0x3c000000, v220
	v_mul_f32_e32 v44, 0x4f800000, v43
	v_cmp_gt_f32_e32 vcc, s39, v43
	v_add_u32_e32 v0, s45, v0
	s_nop 0
	v_cndmask_b32_e32 v43, v43, v44, vcc
	v_sqrt_f32_e32 v44, v43
	s_nop 0
	v_add_u32_e32 v45, -1, v44
	v_fma_f32 v47, -v45, v44, v43
	v_add_u32_e32 v46, 1, v44
	v_cmp_ge_f32_e64 s[0:1], 0, v47
	s_nop 1
	v_cndmask_b32_e64 v45, v44, v45, s[0:1]
	v_fma_f32 v44, -v46, v44, v43
	v_cmp_lt_f32_e64 s[0:1], 0, v44
	s_nop 1
	v_cndmask_b32_e64 v44, v45, v46, s[0:1]
	v_mul_f32_e32 v45, 0x37800000, v44
	v_cndmask_b32_e32 v44, v44, v45, vcc
	v_cmp_class_f32_e32 vcc, v43, v221
	s_nop 1
	v_cndmask_b32_e32 v43, v44, v43, vcc
	v_div_scale_f32 v44, s[0:1], v43, v43, 1.0
	v_rcp_f32_e32 v45, v44
	s_nop 0
	v_fma_f32 v46, -v44, v45, 1.0
	v_fmac_f32_e32 v45, v46, v45
	v_div_scale_f32 v46, vcc, 1.0, v43, 1.0
	v_mul_f32_e32 v47, v46, v45
	v_fma_f32 v48, -v44, v47, v46
	v_fmac_f32_e32 v47, v48, v45
	v_fma_f32 v44, -v44, v47, v46
	v_div_fmas_f32 v44, v44, v45, v47
	v_div_fixup_f32 v43, v44, v43, 1.0
	v_lshlrev_b64 v[44:45], 11, v[0:1]
	v_mul_f32_e32 v0, v33, v43
	v_mul_f32_e32 v0, v11, v0
	v_bfe_u32 v33, v0, 16, 1
	v_lshl_add_u64 v[44:45], v[2:3], 0, v[44:45]
	v_add3_u32 v0, v0, v33, s40
	global_store_short_d16_hi v[44:45], v0, off
	v_mul_f32_e32 v0, v32, v43
	v_mul_f32_e32 v0, v10, v0
	v_bfe_u32 v32, v0, 16, 1
	v_add3_u32 v0, v0, v32, s40
	global_store_short_d16_hi v[44:45], v0, off offset:64
	v_mul_f32_e32 v0, v30, v43
	v_mul_f32_e32 v0, v9, v0
	v_bfe_u32 v30, v0, 16, 1
	v_add3_u32 v0, v0, v30, s40
	global_store_short_d16_hi v[44:45], v0, off offset:128
	v_mul_f32_e32 v0, v31, v43
	v_mul_f32_e32 v0, v8, v0
	v_bfe_u32 v30, v0, 16, 1
	v_add3_u32 v0, v0, v30, s40
	global_store_short_d16_hi v[44:45], v0, off offset:192
.LBB0_730:
	s_or_b64 exec, exec, s[10:11]
	v_add_u32_e32 v0, v13, v201
	ds_read2_b32 v[30:31], v0 offset1:32
	s_waitcnt lgkmcnt(1)
	ds_read2_b32 v[44:45], v0 offset0:64 offset1:96
	s_waitcnt lgkmcnt(1)
	v_add_f32_e32 v32, v55, v31
	v_add_f32_e32 v33, v53, v30
	v_mul_f32_e32 v0, v32, v32
	s_waitcnt lgkmcnt(0)
	v_add_f32_e32 v30, v56, v44
	v_fmac_f32_e32 v0, v33, v33
	v_fmac_f32_e32 v0, v30, v30
	v_add_f32_e32 v31, v54, v45
	v_fmac_f32_e32 v0, v31, v31
	s_nop 1
	s_waitcnt lgkmcnt(0)
	v_add_f32_dpp v0, v0, v0 quad_perm:[1,0,3,2] row_mask:0xf bank_mask:0xf
	s_nop 1
	s_waitcnt lgkmcnt(0)
	v_add_f32_dpp v0, v0, v0 quad_perm:[2,3,0,1] row_mask:0xf bank_mask:0xf
	s_nop 1
	s_waitcnt lgkmcnt(0)
	v_add_f32_dpp v0, v0, v0 row_half_mirror row_mask:0xf bank_mask:0xf
	s_nop 1
	s_waitcnt lgkmcnt(0)
	v_add_f32_dpp v43, v0, v0 row_mirror row_mask:0xf bank_mask:0xf
	ds_swizzle_b32 v44, v43 offset:swizzle(SWAP,16)
	v_add_u32_e32 v0, s46, v200
	v_cmp_gt_u32_e32 vcc, s44, v0
	s_and_saveexec_b64 s[10:11], vcc
	s_cbranch_execz .LBB0_732
	s_waitcnt lgkmcnt(0)
	v_add_f32_e32 v43, v43, v44
	v_fmamk_f32 v43, v43, 0x3c000000, v220
	v_mul_f32_e32 v44, 0x4f800000, v43
	v_cmp_gt_f32_e32 vcc, s39, v43
	v_add_u32_e32 v0, s45, v0
	s_nop 0
	v_cndmask_b32_e32 v43, v43, v44, vcc
	v_sqrt_f32_e32 v44, v43
	s_nop 0
	v_add_u32_e32 v45, -1, v44
	v_fma_f32 v47, -v45, v44, v43
	v_add_u32_e32 v46, 1, v44
	v_cmp_ge_f32_e64 s[0:1], 0, v47
	s_nop 1
	v_cndmask_b32_e64 v45, v44, v45, s[0:1]
	v_fma_f32 v44, -v46, v44, v43
	v_cmp_lt_f32_e64 s[0:1], 0, v44
	s_nop 1
	v_cndmask_b32_e64 v44, v45, v46, s[0:1]
	v_mul_f32_e32 v45, 0x37800000, v44
	v_cndmask_b32_e32 v44, v44, v45, vcc
	v_cmp_class_f32_e32 vcc, v43, v221
	s_nop 1
	v_cndmask_b32_e32 v43, v44, v43, vcc
	v_div_scale_f32 v44, s[0:1], v43, v43, 1.0
	v_rcp_f32_e32 v45, v44
	s_nop 0
	v_fma_f32 v46, -v44, v45, 1.0
	v_fmac_f32_e32 v45, v46, v45
	v_div_scale_f32 v46, vcc, 1.0, v43, 1.0
	v_mul_f32_e32 v47, v46, v45
	v_fma_f32 v48, -v44, v47, v46
	v_fmac_f32_e32 v47, v48, v45
	v_fma_f32 v44, -v44, v47, v46
	v_div_fmas_f32 v44, v44, v45, v47
	v_div_fixup_f32 v43, v44, v43, 1.0
	v_lshlrev_b64 v[44:45], 11, v[0:1]
	v_mul_f32_e32 v0, v33, v43
	v_mul_f32_e32 v0, v11, v0
	v_bfe_u32 v33, v0, 16, 1
	v_lshl_add_u64 v[44:45], v[2:3], 0, v[44:45]
	v_add3_u32 v0, v0, v33, s40
	global_store_short_d16_hi v[44:45], v0, off
	v_mul_f32_e32 v0, v32, v43
	v_mul_f32_e32 v0, v10, v0
	v_bfe_u32 v32, v0, 16, 1
	v_add3_u32 v0, v0, v32, s40
	global_store_short_d16_hi v[44:45], v0, off offset:64
	v_mul_f32_e32 v0, v30, v43
	v_mul_f32_e32 v0, v9, v0
	v_bfe_u32 v30, v0, 16, 1
	v_add3_u32 v0, v0, v30, s40
	global_store_short_d16_hi v[44:45], v0, off offset:128
	v_mul_f32_e32 v0, v31, v43
	v_mul_f32_e32 v0, v8, v0
	v_bfe_u32 v30, v0, 16, 1
	v_add3_u32 v0, v0, v30, s40
	global_store_short_d16_hi v[44:45], v0, off offset:192
; __device__ __forceinline__ unsigned f2bf(float f) { unsigned u = __builtin_bit_cast(unsigned, f); return (u + 0x7fffu + ((u >> 16) & 1u)) >> 16; }
; __device__ __forceinline__ int crow(int r, int hi) { return (r & 3) + 8 * (r >> 2) + 4 * hi; }
; template <int XM> __device__ __forceinline__ float swz_xor(float v) { return __int_as_float(__builtin_amdgcn_ds_swizzle(__float_as_int(v), (XM << 10) | 0x1F)); }
; __device__ __forceinline__ void attn_unit(LAS unsigned char* lds, const bf16_t* Qb, const unsigned char* Kimg, const unsigned char* Vimg, bf16_t* AO, int b, int h, int qpos0, int ntiles, int store_limit, ...
;     ...
;         for (int r = 0; r < 16; ++r) { const int qr = crow(r, hi); float ss = 0.f;
; #pragma unroll
;             for (int d = 0; d < 4; ++d) { o[d][r] += X[qr * 128 + 32 * d + i32]; ss += o[d][r] * o[d][r]; }
;             ss += swz_xor<1>(ss); ss += swz_xor<2>(ss); ss += swz_xor<4>(ss); ss += swz_xor<8>(ss); ss += swz_xor<16>(ss);
;             const float rs = 1.0f / sqrtf(ss * (1.0f / 128.0f) + 1e-5f);
;             const int qp = qp_w + qr;
;             if (qp < store_limit) { bf16_t* op = AO + (rowbase + qp) * DM + h * 128 + i32;
; #pragma unroll
;                 for (int d = 0; d < 4; ++d) op[32 * d] = (bf16_t)f2bf(o[d][r] * rs * sg[d]); } }
.LBB0_732:
	s_or_b64 exec, exec, s[10:11]
	v_add_u32_e32 v0, v13, v203
	ds_read2_b32 v[30:31], v0 offset1:32
	s_waitcnt lgkmcnt(1)
	ds_read2_b32 v[44:45], v0 offset0:64 offset1:96
	s_waitcnt lgkmcnt(1)
	v_add_f32_e32 v32, v51, v31
	v_add_f32_e32 v33, v42, v30
	v_mul_f32_e32 v0, v32, v32
	s_waitcnt lgkmcnt(0)
	v_add_f32_e32 v30, v52, v44
	v_fmac_f32_e32 v0, v33, v33
	v_fmac_f32_e32 v0, v30, v30
	v_add_f32_e32 v31, v50, v45
	v_fmac_f32_e32 v0, v31, v31
	s_nop 1
	s_waitcnt lgkmcnt(0)
	v_add_f32_dpp v0, v0, v0 quad_perm:[1,0,3,2] row_mask:0xf bank_mask:0xf
	s_nop 1
	s_waitcnt lgkmcnt(0)
	v_add_f32_dpp v0, v0, v0 quad_perm:[2,3,0,1] row_mask:0xf bank_mask:0xf
	s_nop 1
	s_waitcnt lgkmcnt(0)
	v_add_f32_dpp v0, v0, v0 row_half_mirror row_mask:0xf bank_mask:0xf
	s_nop 1
	s_waitcnt lgkmcnt(0)
	v_add_f32_dpp v42, v0, v0 row_mirror row_mask:0xf bank_mask:0xf
	ds_swizzle_b32 v43, v42 offset:swizzle(SWAP,16)
	v_add_u32_e32 v0, s46, v202
	v_cmp_gt_u32_e32 vcc, s44, v0
	s_and_saveexec_b64 s[10:11], vcc
	s_cbranch_execz .LBB0_734
	s_waitcnt lgkmcnt(0)
	v_add_f32_e32 v42, v42, v43
	v_fmamk_f32 v42, v42, 0x3c000000, v220
	v_mul_f32_e32 v43, 0x4f800000, v42
	v_cmp_gt_f32_e32 vcc, s39, v42
	v_add_u32_e32 v0, s45, v0
	s_nop 0
	v_cndmask_b32_e32 v42, v42, v43, vcc
	v_sqrt_f32_e32 v43, v42
	s_nop 0
	v_add_u32_e32 v44, -1, v43
	v_fma_f32 v46, -v44, v43, v42
	v_add_u32_e32 v45, 1, v43
	v_cmp_ge_f32_e64 s[0:1], 0, v46
	s_nop 1
	v_cndmask_b32_e64 v44, v43, v44, s[0:1]
	v_fma_f32 v43, -v45, v43, v42
	v_cmp_lt_f32_e64 s[0:1], 0, v43
	s_nop 1
	v_cndmask_b32_e64 v43, v44, v45, s[0:1]
	v_mul_f32_e32 v44, 0x37800000, v43
	v_cndmask_b32_e32 v43, v43, v44, vcc
	v_cmp_class_f32_e32 vcc, v42, v221
	s_nop 1
	v_cndmask_b32_e32 v42, v43, v42, vcc
	v_div_scale_f32 v43, s[0:1], v42, v42, 1.0
	v_rcp_f32_e32 v44, v43
	s_nop 0
	v_fma_f32 v45, -v43, v44, 1.0
	v_fmac_f32_e32 v44, v45, v44
	v_div_scale_f32 v45, vcc, 1.0, v42, 1.0
	v_mul_f32_e32 v46, v45, v44
	v_fma_f32 v47, -v43, v46, v45
	v_fmac_f32_e32 v46, v47, v44
	v_fma_f32 v43, -v43, v46, v45
	v_div_fmas_f32 v43, v43, v44, v46
	v_div_fixup_f32 v44, v43, v42, 1.0
	v_lshlrev_b64 v[42:43], 11, v[0:1]
	v_mul_f32_e32 v0, v33, v44
	v_mul_f32_e32 v0, v11, v0
	v_bfe_u32 v33, v0, 16, 1
	v_lshl_add_u64 v[42:43], v[2:3], 0, v[42:43]
	v_add3_u32 v0, v0, v33, s40
	global_store_short_d16_hi v[42:43], v0, off
	v_mul_f32_e32 v0, v32, v44
	v_mul_f32_e32 v0, v10, v0
	v_bfe_u32 v32, v0, 16, 1
	v_add3_u32 v0, v0, v32, s40
	global_store_short_d16_hi v[42:43], v0, off offset:64
	v_mul_f32_e32 v0, v30, v44
	v_mul_f32_e32 v0, v9, v0
	v_bfe_u32 v30, v0, 16, 1
	v_add3_u32 v0, v0, v30, s40
	global_store_short_d16_hi v[42:43], v0, off offset:128
	v_mul_f32_e32 v0, v31, v44
	v_mul_f32_e32 v0, v8, v0
	v_bfe_u32 v30, v0, 16, 1
	v_add3_u32 v0, v0, v30, s40
	global_store_short_d16_hi v[42:43], v0, off offset:192
.LBB0_734:
	s_or_b64 exec, exec, s[10:11]
	v_add_u32_e32 v0, v13, v205
	ds_read2_b32 v[30:31], v0 offset1:32
	s_waitcnt lgkmcnt(1)
	ds_read2_b32 v[42:43], v0 offset0:64 offset1:96
	s_waitcnt lgkmcnt(1)
	v_add_f32_e32 v32, v40, v31
	v_add_f32_e32 v33, v38, v30
	v_mul_f32_e32 v0, v32, v32
	s_waitcnt lgkmcnt(0)
	v_add_f32_e32 v30, v41, v42
	v_fmac_f32_e32 v0, v33, v33
	v_fmac_f32_e32 v0, v30, v30
	v_add_f32_e32 v31, v39, v43
	v_fmac_f32_e32 v0, v31, v31
	s_nop 1
	s_waitcnt lgkmcnt(0)
	v_add_f32_dpp v0, v0, v0 quad_perm:[1,0,3,2] row_mask:0xf bank_mask:0xf
	s_nop 1
	s_waitcnt lgkmcnt(0)
	v_add_f32_dpp v0, v0, v0 quad_perm:[2,3,0,1] row_mask:0xf bank_mask:0xf
	s_nop 1
	s_waitcnt lgkmcnt(0)
	v_add_f32_dpp v0, v0, v0 row_half_mirror row_mask:0xf bank_mask:0xf
	s_nop 1
	s_waitcnt lgkmcnt(0)
	v_add_f32_dpp v38, v0, v0 row_mirror row_mask:0xf bank_mask:0xf
	ds_swizzle_b32 v39, v38 offset:swizzle(SWAP,16)
	v_add_u32_e32 v0, s46, v204
	v_cmp_gt_u32_e32 vcc, s44, v0
	s_and_saveexec_b64 s[10:11], vcc
	s_cbranch_execz .LBB0_736
	s_waitcnt lgkmcnt(0)
	v_add_f32_e32 v38, v38, v39
	v_fmamk_f32 v38, v38, 0x3c000000, v220
	v_mul_f32_e32 v39, 0x4f800000, v38
	v_cmp_gt_f32_e32 vcc, s39, v38
	v_add_u32_e32 v0, s45, v0
	s_nop 0
	v_cndmask_b32_e32 v38, v38, v39, vcc
	v_sqrt_f32_e32 v39, v38
	s_nop 0
	v_add_u32_e32 v40, -1, v39
	v_fma_f32 v42, -v40, v39, v38
	v_add_u32_e32 v41, 1, v39
	v_cmp_ge_f32_e64 s[0:1], 0, v42
	s_nop 1
	v_cndmask_b32_e64 v40, v39, v40, s[0:1]
	v_fma_f32 v39, -v41, v39, v38
	v_cmp_lt_f32_e64 s[0:1], 0, v39
	s_nop 1
	v_cndmask_b32_e64 v39, v40, v41, s[0:1]
	v_mul_f32_e32 v40, 0x37800000, v39
	v_cndmask_b32_e32 v39, v39, v40, vcc
	v_cmp_class_f32_e32 vcc, v38, v221
	s_nop 1
	v_cndmask_b32_e32 v38, v39, v38, vcc
	v_div_scale_f32 v39, s[0:1], v38, v38, 1.0
	v_rcp_f32_e32 v40, v39
	s_nop 0
	v_fma_f32 v41, -v39, v40, 1.0
	v_fmac_f32_e32 v40, v41, v40
	v_div_scale_f32 v41, vcc, 1.0, v38, 1.0
	v_mul_f32_e32 v42, v41, v40
	v_fma_f32 v43, -v39, v42, v41
	v_fmac_f32_e32 v42, v43, v40
	v_fma_f32 v39, -v39, v42, v41
	v_div_fmas_f32 v39, v39, v40, v42
	v_div_fixup_f32 v40, v39, v38, 1.0
	v_lshlrev_b64 v[38:39], 11, v[0:1]
	v_mul_f32_e32 v0, v33, v40
	v_mul_f32_e32 v0, v11, v0
	v_bfe_u32 v33, v0, 16, 1
	v_lshl_add_u64 v[38:39], v[2:3], 0, v[38:39]
	v_add3_u32 v0, v0, v33, s40
	global_store_short_d16_hi v[38:39], v0, off
	v_mul_f32_e32 v0, v32, v40
	v_mul_f32_e32 v0, v10, v0
	v_bfe_u32 v32, v0, 16, 1
	v_add3_u32 v0, v0, v32, s40
	global_store_short_d16_hi v[38:39], v0, off offset:64
	v_mul_f32_e32 v0, v30, v40
	v_mul_f32_e32 v0, v9, v0
	v_bfe_u32 v30, v0, 16, 1
	v_add3_u32 v0, v0, v30, s40
	global_store_short_d16_hi v[38:39], v0, off offset:128
	v_mul_f32_e32 v0, v31, v40
	v_mul_f32_e32 v0, v8, v0
	v_bfe_u32 v30, v0, 16, 1
	v_add3_u32 v0, v0, v30, s40
	global_store_short_d16_hi v[38:39], v0, off offset:192
; __device__ __forceinline__ unsigned f2bf(float f) { unsigned u = __builtin_bit_cast(unsigned, f); return (u + 0x7fffu + ((u >> 16) & 1u)) >> 16; }
; __device__ __forceinline__ int crow(int r, int hi) { return (r & 3) + 8 * (r >> 2) + 4 * hi; }
; template <int XM> __device__ __forceinline__ float swz_xor(float v) { return __int_as_float(__builtin_amdgcn_ds_swizzle(__float_as_int(v), (XM << 10) | 0x1F)); }
; __device__ __forceinline__ void attn_unit(LAS unsigned char* lds, const bf16_t* Qb, const unsigned char* Kimg, const unsigned char* Vimg, bf16_t* AO, int b, int h, int qpos0, int ntiles, int store_limit, ...
;     ...
;         for (int r = 0; r < 16; ++r) { const int qr = crow(r, hi); float ss = 0.f;
; #pragma unroll
;             for (int d = 0; d < 4; ++d) { o[d][r] += X[qr * 128 + 32 * d + i32]; ss += o[d][r] * o[d][r]; }
;             ss += swz_xor<1>(ss); ss += swz_xor<2>(ss); ss += swz_xor<4>(ss); ss += swz_xor<8>(ss); ss += swz_xor<16>(ss);
;             const float rs = 1.0f / sqrtf(ss * (1.0f / 128.0f) + 1e-5f);
;             const int qp = qp_w + qr;
;             if (qp < store_limit) { bf16_t* op = AO + (rowbase + qp) * DM + h * 128 + i32;
; #pragma unroll
;                 for (int d = 0; d < 4; ++d) op[32 * d] = (bf16_t)f2bf(o[d][r] * rs * sg[d]); } }
.LBB0_736:
	s_or_b64 exec, exec, s[10:11]
	v_add_u32_e32 v0, v13, v207
	ds_read2_b32 v[30:31], v0 offset1:32
	s_waitcnt lgkmcnt(1)
	ds_read2_b32 v[38:39], v0 offset0:64 offset1:96
	s_waitcnt lgkmcnt(1)
	v_add_f32_e32 v32, v36, v31
	v_add_f32_e32 v33, v34, v30
	v_mul_f32_e32 v0, v32, v32
	s_waitcnt lgkmcnt(0)
	v_add_f32_e32 v30, v37, v38
	v_fmac_f32_e32 v0, v33, v33
	v_fmac_f32_e32 v0, v30, v30
	v_add_f32_e32 v31, v35, v39
	v_fmac_f32_e32 v0, v31, v31
	s_nop 1
	s_waitcnt lgkmcnt(0)
	v_add_f32_dpp v0, v0, v0 quad_perm:[1,0,3,2] row_mask:0xf bank_mask:0xf
	s_nop 1
	s_waitcnt lgkmcnt(0)
	v_add_f32_dpp v0, v0, v0 quad_perm:[2,3,0,1] row_mask:0xf bank_mask:0xf
	s_nop 1
	s_waitcnt lgkmcnt(0)
	v_add_f32_dpp v0, v0, v0 row_half_mirror row_mask:0xf bank_mask:0xf
	s_nop 1
	s_waitcnt lgkmcnt(0)
	v_add_f32_dpp v34, v0, v0 row_mirror row_mask:0xf bank_mask:0xf
	ds_swizzle_b32 v35, v34 offset:swizzle(SWAP,16)
	v_add_u32_e32 v0, s46, v206
	v_cmp_gt_u32_e32 vcc, s44, v0
	s_and_saveexec_b64 s[10:11], vcc
	s_cbranch_execz .LBB0_738
	s_waitcnt lgkmcnt(0)
	v_add_f32_e32 v34, v34, v35
	v_fmamk_f32 v34, v34, 0x3c000000, v220
	v_mul_f32_e32 v35, 0x4f800000, v34
	v_cmp_gt_f32_e32 vcc, s39, v34
	v_add_u32_e32 v0, s45, v0
	s_nop 0
	v_cndmask_b32_e32 v34, v34, v35, vcc
	v_sqrt_f32_e32 v35, v34
	s_nop 0
	v_add_u32_e32 v36, -1, v35
	v_fma_f32 v38, -v36, v35, v34
	v_add_u32_e32 v37, 1, v35
	v_cmp_ge_f32_e64 s[0:1], 0, v38
	s_nop 1
	v_cndmask_b32_e64 v36, v35, v36, s[0:1]
	v_fma_f32 v35, -v37, v35, v34
	v_cmp_lt_f32_e64 s[0:1], 0, v35
	s_nop 1
	v_cndmask_b32_e64 v35, v36, v37, s[0:1]
	v_mul_f32_e32 v36, 0x37800000, v35
	v_cndmask_b32_e32 v35, v35, v36, vcc
	v_cmp_class_f32_e32 vcc, v34, v221
	s_nop 1
	v_cndmask_b32_e32 v34, v35, v34, vcc
	v_div_scale_f32 v35, s[0:1], v34, v34, 1.0
	v_rcp_f32_e32 v36, v35
	s_nop 0
	v_fma_f32 v37, -v35, v36, 1.0
	v_fmac_f32_e32 v36, v37, v36
	v_div_scale_f32 v37, vcc, 1.0, v34, 1.0
	v_mul_f32_e32 v38, v37, v36
	v_fma_f32 v39, -v35, v38, v37
	v_fmac_f32_e32 v38, v39, v36
	v_fma_f32 v35, -v35, v38, v37
	v_div_fmas_f32 v35, v35, v36, v38
	v_div_fixup_f32 v36, v35, v34, 1.0
	v_lshlrev_b64 v[34:35], 11, v[0:1]
	v_mul_f32_e32 v0, v33, v36
	v_mul_f32_e32 v0, v11, v0
	v_bfe_u32 v33, v0, 16, 1
	v_lshl_add_u64 v[34:35], v[2:3], 0, v[34:35]
	v_add3_u32 v0, v0, v33, s40
	global_store_short_d16_hi v[34:35], v0, off
	v_mul_f32_e32 v0, v32, v36
	v_mul_f32_e32 v0, v10, v0
	v_bfe_u32 v32, v0, 16, 1
	v_add3_u32 v0, v0, v32, s40
	global_store_short_d16_hi v[34:35], v0, off offset:64
	v_mul_f32_e32 v0, v30, v36
	v_mul_f32_e32 v0, v9, v0
	v_bfe_u32 v30, v0, 16, 1
	v_add3_u32 v0, v0, v30, s40
	global_store_short_d16_hi v[34:35], v0, off offset:128
	v_mul_f32_e32 v0, v31, v36
	v_mul_f32_e32 v0, v8, v0
	v_bfe_u32 v30, v0, 16, 1
	v_add3_u32 v0, v0, v30, s40
	global_store_short_d16_hi v[34:35], v0, off offset:192
.LBB0_738:
	s_or_b64 exec, exec, s[10:11]
	v_add_u32_e32 v0, v13, v209
	ds_read2_b32 v[30:31], v0 offset1:32
	ds_read2_b32 v[32:33], v0 offset0:64 offset1:96
	s_waitcnt lgkmcnt(1)
	v_add_f32_e32 v28, v28, v31
	v_add_f32_e32 v30, v26, v30
	v_mul_f32_e32 v0, v28, v28
	s_waitcnt lgkmcnt(0)
	v_add_f32_e32 v26, v29, v32
	v_fmac_f32_e32 v0, v30, v30
	v_fmac_f32_e32 v0, v26, v26
	v_add_f32_e32 v27, v27, v33
	v_fmac_f32_e32 v0, v27, v27
	s_nop 1
	s_waitcnt lgkmcnt(0)
	v_add_f32_dpp v0, v0, v0 quad_perm:[1,0,3,2] row_mask:0xf bank_mask:0xf
	s_nop 1
	s_waitcnt lgkmcnt(0)
	v_add_f32_dpp v0, v0, v0 quad_perm:[2,3,0,1] row_mask:0xf bank_mask:0xf
	s_nop 1
	s_waitcnt lgkmcnt(0)
	v_add_f32_dpp v0, v0, v0 row_half_mirror row_mask:0xf bank_mask:0xf
	s_nop 1
	s_waitcnt lgkmcnt(0)
	v_add_f32_dpp v29, v0, v0 row_mirror row_mask:0xf bank_mask:0xf
	ds_swizzle_b32 v31, v29 offset:swizzle(SWAP,16)
	v_add_u32_e32 v0, s46, v208
	v_cmp_gt_u32_e32 vcc, s44, v0
	s_and_saveexec_b64 s[10:11], vcc
	s_cbranch_execz .LBB0_740
	s_waitcnt lgkmcnt(0)
	v_add_f32_e32 v29, v29, v31
	v_fmamk_f32 v29, v29, 0x3c000000, v220
	v_mul_f32_e32 v31, 0x4f800000, v29
	v_cmp_gt_f32_e32 vcc, s39, v29
	v_add_u32_e32 v0, s45, v0
	s_nop 0
	v_cndmask_b32_e32 v29, v29, v31, vcc
	v_sqrt_f32_e32 v31, v29
	s_nop 0
	v_add_u32_e32 v32, -1, v31
	v_fma_f32 v34, -v32, v31, v29
	v_add_u32_e32 v33, 1, v31
	v_cmp_ge_f32_e64 s[0:1], 0, v34
	s_nop 1
	v_cndmask_b32_e64 v32, v31, v32, s[0:1]
	v_fma_f32 v31, -v33, v31, v29
	v_cmp_lt_f32_e64 s[0:1], 0, v31
	s_nop 1
	v_cndmask_b32_e64 v31, v32, v33, s[0:1]
	v_mul_f32_e32 v32, 0x37800000, v31
	v_cndmask_b32_e32 v31, v31, v32, vcc
	v_cmp_class_f32_e32 vcc, v29, v221
	s_nop 1
	v_cndmask_b32_e32 v29, v31, v29, vcc
	v_div_scale_f32 v31, s[0:1], v29, v29, 1.0
	v_rcp_f32_e32 v32, v31
	s_nop 0
	v_fma_f32 v33, -v31, v32, 1.0
	v_fmac_f32_e32 v32, v33, v32
	v_div_scale_f32 v33, vcc, 1.0, v29, 1.0
	v_mul_f32_e32 v34, v33, v32
	v_fma_f32 v35, -v31, v34, v33
	v_fmac_f32_e32 v34, v35, v32
	v_fma_f32 v31, -v31, v34, v33
	v_div_fmas_f32 v31, v31, v32, v34
	v_div_fixup_f32 v29, v31, v29, 1.0
	v_lshlrev_b64 v[32:33], 11, v[0:1]
	v_mul_f32_e32 v0, v30, v29
	v_mul_f32_e32 v0, v11, v0
	v_bfe_u32 v30, v0, 16, 1
	v_lshl_add_u64 v[32:33], v[2:3], 0, v[32:33]
	v_add3_u32 v0, v0, v30, s40
	global_store_short_d16_hi v[32:33], v0, off
	v_mul_f32_e32 v0, v28, v29
	v_mul_f32_e32 v0, v10, v0
	v_bfe_u32 v28, v0, 16, 1
	v_add3_u32 v0, v0, v28, s40
	global_store_short_d16_hi v[32:33], v0, off offset:64
	v_mul_f32_e32 v0, v26, v29
	v_mul_f32_e32 v0, v9, v0
	v_bfe_u32 v26, v0, 16, 1
	v_add3_u32 v0, v0, v26, s40
	global_store_short_d16_hi v[32:33], v0, off offset:128
	v_mul_f32_e32 v0, v27, v29
	v_mul_f32_e32 v0, v8, v0
	v_bfe_u32 v26, v0, 16, 1
	v_add3_u32 v0, v0, v26, s40
	global_store_short_d16_hi v[32:33], v0, off offset:192
; __device__ __forceinline__ unsigned f2bf(float f) { unsigned u = __builtin_bit_cast(unsigned, f); return (u + 0x7fffu + ((u >> 16) & 1u)) >> 16; }
; __device__ __forceinline__ int crow(int r, int hi) { return (r & 3) + 8 * (r >> 2) + 4 * hi; }
; template <int XM> __device__ __forceinline__ float swz_xor(float v) { return __int_as_float(__builtin_amdgcn_ds_swizzle(__float_as_int(v), (XM << 10) | 0x1F)); }
; __device__ __forceinline__ void attn_unit(LAS unsigned char* lds, const bf16_t* Qb, const unsigned char* Kimg, const unsigned char* Vimg, bf16_t* AO, int b, int h, int qpos0, int ntiles, int store_limit, ...
;     ...
;         for (int r = 0; r < 16; ++r) { const int qr = crow(r, hi); float ss = 0.f;
; #pragma unroll
;             for (int d = 0; d < 4; ++d) { o[d][r] += X[qr * 128 + 32 * d + i32]; ss += o[d][r] * o[d][r]; }
;             ss += swz_xor<1>(ss); ss += swz_xor<2>(ss); ss += swz_xor<4>(ss); ss += swz_xor<8>(ss); ss += swz_xor<16>(ss);
;             const float rs = 1.0f / sqrtf(ss * (1.0f / 128.0f) + 1e-5f);
;             const int qp = qp_w + qr;
;             if (qp < store_limit) { bf16_t* op = AO + (rowbase + qp) * DM + h * 128 + i32;
; #pragma unroll
;                 for (int d = 0; d < 4; ++d) op[32 * d] = (bf16_t)f2bf(o[d][r] * rs * sg[d]); } }
.LBB0_740:
	s_or_b64 exec, exec, s[10:11]
	v_add_u32_e32 v0, v13, v211
	ds_read2_b32 v[26:27], v0 offset1:32
	ds_read2_b32 v[28:29], v0 offset0:64 offset1:96
	s_waitcnt lgkmcnt(1)
	v_add_f32_e32 v24, v24, v27
	v_add_f32_e32 v26, v22, v26
	v_mul_f32_e32 v0, v24, v24
	s_waitcnt lgkmcnt(0)
	v_add_f32_e32 v22, v25, v28
	v_fmac_f32_e32 v0, v26, v26
	v_fmac_f32_e32 v0, v22, v22
	v_add_f32_e32 v23, v23, v29
	v_fmac_f32_e32 v0, v23, v23
	s_nop 1
	s_waitcnt lgkmcnt(0)
	v_add_f32_dpp v0, v0, v0 quad_perm:[1,0,3,2] row_mask:0xf bank_mask:0xf
	s_nop 1
	s_waitcnt lgkmcnt(0)
	v_add_f32_dpp v0, v0, v0 quad_perm:[2,3,0,1] row_mask:0xf bank_mask:0xf
	s_nop 1
	s_waitcnt lgkmcnt(0)
	v_add_f32_dpp v0, v0, v0 row_half_mirror row_mask:0xf bank_mask:0xf
	s_nop 1
	s_waitcnt lgkmcnt(0)
	v_add_f32_dpp v25, v0, v0 row_mirror row_mask:0xf bank_mask:0xf
	ds_swizzle_b32 v27, v25 offset:swizzle(SWAP,16)
	v_add_u32_e32 v0, s46, v210
	v_cmp_gt_u32_e32 vcc, s44, v0
	s_and_saveexec_b64 s[10:11], vcc
	s_cbranch_execz .LBB0_742
	s_waitcnt lgkmcnt(0)
	v_add_f32_e32 v25, v25, v27
	v_fmamk_f32 v25, v25, 0x3c000000, v220
	v_mul_f32_e32 v27, 0x4f800000, v25
	v_cmp_gt_f32_e32 vcc, s39, v25
	v_add_u32_e32 v0, s45, v0
	s_nop 0
	v_cndmask_b32_e32 v25, v25, v27, vcc
	v_sqrt_f32_e32 v27, v25
	s_nop 0
	v_add_u32_e32 v28, -1, v27
	v_fma_f32 v30, -v28, v27, v25
	v_add_u32_e32 v29, 1, v27
	v_cmp_ge_f32_e64 s[0:1], 0, v30
	s_nop 1
	v_cndmask_b32_e64 v28, v27, v28, s[0:1]
	v_fma_f32 v27, -v29, v27, v25
	v_cmp_lt_f32_e64 s[0:1], 0, v27
	s_nop 1
	v_cndmask_b32_e64 v27, v28, v29, s[0:1]
	v_mul_f32_e32 v28, 0x37800000, v27
	v_cndmask_b32_e32 v27, v27, v28, vcc
	v_cmp_class_f32_e32 vcc, v25, v221
	s_nop 1
	v_cndmask_b32_e32 v25, v27, v25, vcc
	v_div_scale_f32 v27, s[0:1], v25, v25, 1.0
	v_rcp_f32_e32 v28, v27
	s_nop 0
	v_fma_f32 v29, -v27, v28, 1.0
	v_fmac_f32_e32 v28, v29, v28
	v_div_scale_f32 v29, vcc, 1.0, v25, 1.0
	v_mul_f32_e32 v30, v29, v28
	v_fma_f32 v31, -v27, v30, v29
	v_fmac_f32_e32 v30, v31, v28
	v_fma_f32 v27, -v27, v30, v29
	v_div_fmas_f32 v27, v27, v28, v30
	v_div_fixup_f32 v25, v27, v25, 1.0
	v_lshlrev_b64 v[28:29], 11, v[0:1]
	v_mul_f32_e32 v0, v26, v25
	v_mul_f32_e32 v0, v11, v0
	v_bfe_u32 v26, v0, 16, 1
	v_lshl_add_u64 v[28:29], v[2:3], 0, v[28:29]
	v_add3_u32 v0, v0, v26, s40
	global_store_short_d16_hi v[28:29], v0, off
	v_mul_f32_e32 v0, v24, v25
	v_mul_f32_e32 v0, v10, v0
	v_bfe_u32 v24, v0, 16, 1
	v_add3_u32 v0, v0, v24, s40
	global_store_short_d16_hi v[28:29], v0, off offset:64
	v_mul_f32_e32 v0, v22, v25
	v_mul_f32_e32 v0, v9, v0
	v_bfe_u32 v22, v0, 16, 1
	v_add3_u32 v0, v0, v22, s40
	global_store_short_d16_hi v[28:29], v0, off offset:128
	v_mul_f32_e32 v0, v23, v25
	v_mul_f32_e32 v0, v8, v0
	v_bfe_u32 v22, v0, 16, 1
	v_add3_u32 v0, v0, v22, s40
	global_store_short_d16_hi v[28:29], v0, off offset:192
.LBB0_742:
	s_or_b64 exec, exec, s[10:11]
	v_add_u32_e32 v0, v13, v213
	ds_read2_b32 v[22:23], v0 offset1:32
	ds_read2_b32 v[24:25], v0 offset0:64 offset1:96
	s_waitcnt lgkmcnt(1)
	v_add_f32_e32 v20, v20, v23
	v_add_f32_e32 v22, v18, v22
	v_mul_f32_e32 v0, v20, v20
	s_waitcnt lgkmcnt(0)
	v_add_f32_e32 v18, v21, v24
	v_fmac_f32_e32 v0, v22, v22
	v_fmac_f32_e32 v0, v18, v18
	v_add_f32_e32 v19, v19, v25
	v_fmac_f32_e32 v0, v19, v19
	s_nop 1
	s_waitcnt lgkmcnt(0)
	v_add_f32_dpp v0, v0, v0 quad_perm:[1,0,3,2] row_mask:0xf bank_mask:0xf
	s_nop 1
	s_waitcnt lgkmcnt(0)
	v_add_f32_dpp v0, v0, v0 quad_perm:[2,3,0,1] row_mask:0xf bank_mask:0xf
	s_nop 1
	s_waitcnt lgkmcnt(0)
	v_add_f32_dpp v0, v0, v0 row_half_mirror row_mask:0xf bank_mask:0xf
	s_nop 1
	s_waitcnt lgkmcnt(0)
	v_add_f32_dpp v21, v0, v0 row_mirror row_mask:0xf bank_mask:0xf
	ds_swizzle_b32 v23, v21 offset:swizzle(SWAP,16)
	v_add_u32_e32 v0, s46, v212
	v_cmp_gt_u32_e32 vcc, s44, v0
	s_and_saveexec_b64 s[10:11], vcc
	s_cbranch_execz .LBB0_744
	s_waitcnt lgkmcnt(0)
	v_add_f32_e32 v21, v21, v23
	v_fmamk_f32 v21, v21, 0x3c000000, v220
	v_mul_f32_e32 v23, 0x4f800000, v21
	v_cmp_gt_f32_e32 vcc, s39, v21
	v_add_u32_e32 v0, s45, v0
	s_nop 0
	v_cndmask_b32_e32 v21, v21, v23, vcc
	v_sqrt_f32_e32 v23, v21
	s_nop 0
	v_add_u32_e32 v24, -1, v23
	v_fma_f32 v26, -v24, v23, v21
	v_add_u32_e32 v25, 1, v23
	v_cmp_ge_f32_e64 s[0:1], 0, v26
	s_nop 1
	v_cndmask_b32_e64 v24, v23, v24, s[0:1]
	v_fma_f32 v23, -v25, v23, v21
	v_cmp_lt_f32_e64 s[0:1], 0, v23
	s_nop 1
	v_cndmask_b32_e64 v23, v24, v25, s[0:1]
	v_mul_f32_e32 v24, 0x37800000, v23
	v_cndmask_b32_e32 v23, v23, v24, vcc
	v_cmp_class_f32_e32 vcc, v21, v221
	s_nop 1
	v_cndmask_b32_e32 v21, v23, v21, vcc
	v_div_scale_f32 v23, s[0:1], v21, v21, 1.0
	v_rcp_f32_e32 v24, v23
	s_nop 0
	v_fma_f32 v25, -v23, v24, 1.0
	v_fmac_f32_e32 v24, v25, v24
	v_div_scale_f32 v25, vcc, 1.0, v21, 1.0
	v_mul_f32_e32 v26, v25, v24
	v_fma_f32 v27, -v23, v26, v25
	v_fmac_f32_e32 v26, v27, v24
	v_fma_f32 v23, -v23, v26, v25
	v_div_fmas_f32 v23, v23, v24, v26
	v_div_fixup_f32 v21, v23, v21, 1.0
	v_lshlrev_b64 v[24:25], 11, v[0:1]
	v_mul_f32_e32 v0, v22, v21
	v_mul_f32_e32 v0, v11, v0
	v_bfe_u32 v22, v0, 16, 1
	v_lshl_add_u64 v[24:25], v[2:3], 0, v[24:25]
	v_add3_u32 v0, v0, v22, s40
	global_store_short_d16_hi v[24:25], v0, off
	v_mul_f32_e32 v0, v20, v21
	v_mul_f32_e32 v0, v10, v0
	v_bfe_u32 v20, v0, 16, 1
	v_add3_u32 v0, v0, v20, s40
	global_store_short_d16_hi v[24:25], v0, off offset:64
	v_mul_f32_e32 v0, v18, v21
	v_mul_f32_e32 v0, v9, v0
	v_bfe_u32 v18, v0, 16, 1
	v_add3_u32 v0, v0, v18, s40
	global_store_short_d16_hi v[24:25], v0, off offset:128
	v_mul_f32_e32 v0, v19, v21
	v_mul_f32_e32 v0, v8, v0
	v_bfe_u32 v18, v0, 16, 1
	v_add3_u32 v0, v0, v18, s40
	global_store_short_d16_hi v[24:25], v0, off offset:192
; __device__ __forceinline__ unsigned f2bf(float f) { unsigned u = __builtin_bit_cast(unsigned, f); return (u + 0x7fffu + ((u >> 16) & 1u)) >> 16; }
; __device__ __forceinline__ int crow(int r, int hi) { return (r & 3) + 8 * (r >> 2) + 4 * hi; }
; template <int XM> __device__ __forceinline__ float swz_xor(float v) { return __int_as_float(__builtin_amdgcn_ds_swizzle(__float_as_int(v), (XM << 10) | 0x1F)); }
; __device__ __forceinline__ void attn_unit(LAS unsigned char* lds, const bf16_t* Qb, const unsigned char* Kimg, const unsigned char* Vimg, bf16_t* AO, int b, int h, int qpos0, int ntiles, int store_limit, ...
;     ...
;         for (int r = 0; r < 16; ++r) { const int qr = crow(r, hi); float ss = 0.f;
; #pragma unroll
;             for (int d = 0; d < 4; ++d) { o[d][r] += X[qr * 128 + 32 * d + i32]; ss += o[d][r] * o[d][r]; }
;             ss += swz_xor<1>(ss); ss += swz_xor<2>(ss); ss += swz_xor<4>(ss); ss += swz_xor<8>(ss); ss += swz_xor<16>(ss);
;             const float rs = 1.0f / sqrtf(ss * (1.0f / 128.0f) + 1e-5f);
;             const int qp = qp_w + qr;
;             if (qp < store_limit) { bf16_t* op = AO + (rowbase + qp) * DM + h * 128 + i32;
; #pragma unroll
;                 for (int d = 0; d < 4; ++d) op[32 * d] = (bf16_t)f2bf(o[d][r] * rs * sg[d]); } }
.LBB0_744:
	s_or_b64 exec, exec, s[10:11]
	v_add_u32_e32 v0, v13, v215
	ds_read2_b32 v[18:19], v0 offset1:32
	ds_read2_b32 v[20:21], v0 offset0:64 offset1:96
	s_waitcnt lgkmcnt(1)
	v_add_f32_e32 v15, v15, v19
	v_add_f32_e32 v18, v12, v18
	v_mul_f32_e32 v0, v15, v15
	s_waitcnt lgkmcnt(0)
	v_add_f32_e32 v12, v17, v20
	v_fmac_f32_e32 v0, v18, v18
	v_fmac_f32_e32 v0, v12, v12
	v_add_f32_e32 v14, v14, v21
	v_fmac_f32_e32 v0, v14, v14
	s_nop 1
	s_waitcnt lgkmcnt(0)
	v_add_f32_dpp v0, v0, v0 quad_perm:[1,0,3,2] row_mask:0xf bank_mask:0xf
	s_nop 1
	s_waitcnt lgkmcnt(0)
	v_add_f32_dpp v0, v0, v0 quad_perm:[2,3,0,1] row_mask:0xf bank_mask:0xf
	s_nop 1
	s_waitcnt lgkmcnt(0)
	v_add_f32_dpp v0, v0, v0 row_half_mirror row_mask:0xf bank_mask:0xf
	s_nop 1
	s_waitcnt lgkmcnt(0)
	v_add_f32_dpp v17, v0, v0 row_mirror row_mask:0xf bank_mask:0xf
	ds_swizzle_b32 v19, v17 offset:swizzle(SWAP,16)
	v_add_u32_e32 v0, s46, v214
	v_cmp_gt_u32_e32 vcc, s44, v0
	s_and_saveexec_b64 s[10:11], vcc
	s_cbranch_execz .LBB0_746
	s_waitcnt lgkmcnt(0)
	v_add_f32_e32 v17, v17, v19
	v_fmamk_f32 v17, v17, 0x3c000000, v220
	v_mul_f32_e32 v19, 0x4f800000, v17
	v_cmp_gt_f32_e32 vcc, s39, v17
	v_add_u32_e32 v0, s45, v0
	s_nop 0
	v_cndmask_b32_e32 v17, v17, v19, vcc
	v_sqrt_f32_e32 v19, v17
	s_nop 0
	v_add_u32_e32 v20, -1, v19
	v_fma_f32 v22, -v20, v19, v17
	v_add_u32_e32 v21, 1, v19
	v_cmp_ge_f32_e64 s[0:1], 0, v22
	s_nop 1
	v_cndmask_b32_e64 v20, v19, v20, s[0:1]
	v_fma_f32 v19, -v21, v19, v17
	v_cmp_lt_f32_e64 s[0:1], 0, v19
	s_nop 1
	v_cndmask_b32_e64 v19, v20, v21, s[0:1]
	v_mul_f32_e32 v20, 0x37800000, v19
	v_cndmask_b32_e32 v19, v19, v20, vcc
	v_cmp_class_f32_e32 vcc, v17, v221
	s_nop 1
	v_cndmask_b32_e32 v17, v19, v17, vcc
	v_div_scale_f32 v19, s[0:1], v17, v17, 1.0
	v_rcp_f32_e32 v20, v19
	s_nop 0
	v_fma_f32 v21, -v19, v20, 1.0
	v_fmac_f32_e32 v20, v21, v20
	v_div_scale_f32 v21, vcc, 1.0, v17, 1.0
	v_mul_f32_e32 v22, v21, v20
	v_fma_f32 v23, -v19, v22, v21
	v_fmac_f32_e32 v22, v23, v20
	v_fma_f32 v19, -v19, v22, v21
	v_div_fmas_f32 v19, v19, v20, v22
	v_div_fixup_f32 v17, v19, v17, 1.0
	v_lshlrev_b64 v[20:21], 11, v[0:1]
	v_mul_f32_e32 v0, v18, v17
	v_mul_f32_e32 v0, v11, v0
	v_bfe_u32 v18, v0, 16, 1
	v_lshl_add_u64 v[20:21], v[2:3], 0, v[20:21]
	v_add3_u32 v0, v0, v18, s40
	global_store_short_d16_hi v[20:21], v0, off
	v_mul_f32_e32 v0, v15, v17
	v_mul_f32_e32 v0, v10, v0
	v_bfe_u32 v15, v0, 16, 1
	v_add3_u32 v0, v0, v15, s40
	global_store_short_d16_hi v[20:21], v0, off offset:64
	v_mul_f32_e32 v0, v12, v17
	v_mul_f32_e32 v0, v9, v0
	v_bfe_u32 v12, v0, 16, 1
	v_add3_u32 v0, v0, v12, s40
	global_store_short_d16_hi v[20:21], v0, off offset:128
	v_mul_f32_e32 v0, v14, v17
	v_mul_f32_e32 v0, v8, v0
	v_bfe_u32 v12, v0, 16, 1
	v_add3_u32 v0, v0, v12, s40
	global_store_short_d16_hi v[20:21], v0, off offset:192
.LBB0_746:
	s_or_b64 exec, exec, s[10:11]
	v_add_u32_e32 v0, v13, v217
	ds_read2_b32 v[14:15], v0 offset1:32
	s_waitcnt lgkmcnt(1)
	ds_read2_b32 v[18:19], v0 offset0:64 offset1:96
	s_waitcnt lgkmcnt(1)
	v_add_f32_e32 v12, v5, v15
	v_add_f32_e32 v13, v4, v14
	v_mul_f32_e32 v0, v12, v12
	s_waitcnt lgkmcnt(0)
	v_add_f32_e32 v4, v6, v18
	v_fmac_f32_e32 v0, v13, v13
	v_fmac_f32_e32 v0, v4, v4
	v_add_f32_e32 v5, v7, v19
	v_fmac_f32_e32 v0, v5, v5
	s_nop 1
	s_waitcnt lgkmcnt(0)
	v_add_f32_dpp v0, v0, v0 quad_perm:[1,0,3,2] row_mask:0xf bank_mask:0xf
	s_nop 1
	s_waitcnt lgkmcnt(0)
	v_add_f32_dpp v0, v0, v0 quad_perm:[2,3,0,1] row_mask:0xf bank_mask:0xf
	s_nop 1
	s_waitcnt lgkmcnt(0)
	v_add_f32_dpp v0, v0, v0 row_half_mirror row_mask:0xf bank_mask:0xf
	s_nop 1
	s_waitcnt lgkmcnt(0)
	v_add_f32_dpp v6, v0, v0 row_mirror row_mask:0xf bank_mask:0xf
	ds_swizzle_b32 v7, v6 offset:swizzle(SWAP,16)
	v_add_u32_e32 v0, s46, v216
	v_cmp_gt_u32_e32 vcc, s44, v0
	s_and_saveexec_b64 s[10:11], vcc
	s_cbranch_execz .LBB0_748
	s_waitcnt lgkmcnt(0)
	v_add_f32_e32 v6, v6, v7
	v_fmamk_f32 v6, v6, 0x3c000000, v220
	v_mul_f32_e32 v7, 0x4f800000, v6
	v_cmp_gt_f32_e32 vcc, s39, v6
	v_add_u32_e32 v0, s45, v0
	s_nop 0
	v_cndmask_b32_e32 v6, v6, v7, vcc
	v_sqrt_f32_e32 v7, v6
	s_nop 0
	v_add_u32_e32 v14, -1, v7
	v_fma_f32 v17, -v14, v7, v6
	v_add_u32_e32 v15, 1, v7
	v_cmp_ge_f32_e64 s[0:1], 0, v17
	s_nop 1
	v_cndmask_b32_e64 v14, v7, v14, s[0:1]
	v_fma_f32 v7, -v15, v7, v6
	v_cmp_lt_f32_e64 s[0:1], 0, v7
	s_nop 1
	v_cndmask_b32_e64 v7, v14, v15, s[0:1]
	v_mul_f32_e32 v14, 0x37800000, v7
	v_cndmask_b32_e32 v7, v7, v14, vcc
	v_cmp_class_f32_e32 vcc, v6, v221
	s_nop 1
	v_cndmask_b32_e32 v6, v7, v6, vcc
	v_div_scale_f32 v7, s[0:1], v6, v6, 1.0
	v_rcp_f32_e32 v14, v7
	s_nop 0
	v_fma_f32 v15, -v7, v14, 1.0
	v_fmac_f32_e32 v14, v15, v14
	v_div_scale_f32 v15, vcc, 1.0, v6, 1.0
	v_mul_f32_e32 v17, v15, v14
	v_fma_f32 v18, -v7, v17, v15
	v_fmac_f32_e32 v17, v18, v14
	v_fma_f32 v7, -v7, v17, v15
	v_div_fmas_f32 v7, v7, v14, v17
	v_div_fixup_f32 v14, v7, v6, 1.0
	v_lshlrev_b64 v[6:7], 11, v[0:1]
	v_mul_f32_e32 v0, v13, v14
	v_mul_f32_e32 v0, v11, v0
	v_lshl_add_u64 v[2:3], v[2:3], 0, v[6:7]
	v_bfe_u32 v6, v0, 16, 1
	v_add3_u32 v0, v0, v6, s40
	global_store_short_d16_hi v[2:3], v0, off
	v_mul_f32_e32 v0, v12, v14
	v_mul_f32_e32 v0, v10, v0
	v_bfe_u32 v6, v0, 16, 1
	v_add3_u32 v0, v0, v6, s40
	global_store_short_d16_hi v[2:3], v0, off offset:64
	v_mul_f32_e32 v0, v4, v14
	v_mul_f32_e32 v0, v9, v0
	v_bfe_u32 v4, v0, 16, 1
	v_add3_u32 v0, v0, v4, s40
	global_store_short_d16_hi v[2:3], v0, off offset:128
	v_mul_f32_e32 v0, v5, v14
	v_mul_f32_e32 v0, v8, v0
	v_bfe_u32 v4, v0, 16, 1
	v_add3_u32 v0, v0, v4, s40
	global_store_short_d16_hi v[2:3], v0, off offset:192
